# v20: v16 + the packed f32 ops (v_pk_mul/add/fma_f32) of the P1 epilogues split into their two scalar f32 ops
# baseline (speedup 1.0000x reference)
; __device__ __forceinline__ u32x4 pack8(f32x4 v0, f32x4 v1) { u32x4 w; w.x = cvt_pk_bf16(v0[0], v0[1]); w.y = cvt_pk_bf16(v0[2], v0[3]); w.z = cvt_pk_bf16(v1[0], v1[1]); w.w = cvt_pk_bf16(v1[2], v1[3]); return w; }
; __device__ __forceinline__ f32x4 sigmoid4(f32x4 v) { const f32x2 a = sigmoid2((f32x2){v[0], v[1]}), b = sigmoid2((f32x2){v[2], v[3]}); return (f32x4){a.x, a.y, b.x, b.y}; }
; __device__ __forceinline__ f32x2 sigmoid2(f32x2 x) { const f32x2 t = x * (-LOG2E); f32x2 e; e.x = __builtin_amdgcn_exp2f(t.x); e.y = __builtin_amdgcn_exp2f(t.y);
;     const f32x2 d = e + 1.0f; f32x2 r; r.x = __builtin_amdgcn_rcpf(d.x); r.y = __builtin_amdgcn_rcpf(d.y); return r; }
;     __device__ __forceinline__ void operator()(const f32x4 (&acc)[2][2][4][2], const Unit& u, int ui, int wr, int wc, int fr, int fq) const {
;     ...
;         bf16_t* base; size_t ld; int row0, col0, act;
;         if (pn < 12)      { base = (bf16_t*)(ws + WS_Q);  ld = DM;  row0 = u.pm * 256; col0 = (pn - 8) * 256;  act = 0; }
;         else if (pn < 13) { base = (bf16_t*)(ws + WS_K);  ld = 256; row0 = u.pm * 256; col0 = 0;               act = 0; }
;         else if (pn < 17) { base = (bf16_t*)(ws + WS_SB); ld = DM;  row0 = u.pm * 256; col0 = (pn - 13) * 256; act = 2; }
;         else              { base = (bf16_t*)(ws + WS_VT); ld = MTOK; row0 = 0; col0 = u.pm * 256; act = 0; }
;         const int r0 = row0 + wr * 64 + fr, c0 = col0 + wc * 32 + 8 * fq;
; #pragma unroll
;         for (int ai = 0; ai < 2; ++ai)
; #pragma unroll
;             for (int m = 0; m < 4; ++m) { bf16_t* rowp = base + (size_t)(r0 + ai * 128 + m * 16) * ld + c0;
; #pragma unroll
;                 for (int bj = 0; bj < 2; ++bj) { f32x4 v0 = acc[ai][bj][m][0], v1 = acc[ai][bj][m][1];
;                     if (act == 2) { v0 = sigmoid4(v0); v1 = sigmoid4(v1); }
;                     *(u32x4*)(rowp + bj * 128) = pack8(v0, v1); } }
.LBB0_137:
	v_cndmask_b32_e64 v140, 0, 1, s[82:83]
	v_cmp_ne_u32_e64 s[6:7], 1, v140
	s_andn2_b64 vcc, exec, s[82:83]
	v_mov_b32_e32 v155, v120
	v_mov_b32_e32 v156, v121
	v_mov_b32_e32 v157, v122
	v_mov_b32_e32 v158, v123
	v_mov_b32_e32 v159, v116
	v_mov_b32_e32 v160, v117
	v_mov_b32_e32 v161, v118
	v_mov_b32_e32 v162, v119
	s_cbranch_vccnz .LBB0_139
	v_mul_f32_e32 v150, s60, v120
	v_mul_f32_e32 v151, s60, v121
	s_nop 0
	v_exp_f32_e32 v150, v150
	v_exp_f32_e32 v151, v151
	s_nop 0
	v_add_f32_e32 v150, 1.0, v150
	v_add_f32_e32 v151, 1.0, v151
	s_nop 0
	v_rcp_f32_e32 v155, v150
	v_rcp_f32_e32 v156, v151
	v_mul_f32_e32 v150, s60, v122
	v_mul_f32_e32 v151, s60, v123
	s_nop 0
	v_exp_f32_e32 v150, v150
	v_exp_f32_e32 v151, v151
	s_nop 0
	v_add_f32_e32 v150, 1.0, v150
	v_add_f32_e32 v151, 1.0, v151
	s_nop 0
	v_rcp_f32_e32 v157, v150
	v_rcp_f32_e32 v158, v151
	v_mul_f32_e32 v150, s60, v116
	v_mul_f32_e32 v151, s60, v117
	s_nop 0
	v_exp_f32_e32 v150, v150
	v_exp_f32_e32 v151, v151
	s_nop 0
	v_add_f32_e32 v150, 1.0, v150
	v_add_f32_e32 v151, 1.0, v151
	s_nop 0
	v_rcp_f32_e32 v159, v150
	v_rcp_f32_e32 v160, v151
	v_mul_f32_e32 v150, s60, v118
	v_mul_f32_e32 v151, s60, v119
	s_nop 0
	v_exp_f32_e32 v150, v150
	v_exp_f32_e32 v151, v151
	s_nop 0
	v_add_f32_e32 v150, 1.0, v150
	v_add_f32_e32 v151, 1.0, v151
	s_nop 0
	v_rcp_f32_e32 v161, v150
	v_rcp_f32_e32 v162, v151
.LBB0_139:
	v_add_u32_e32 v150, s20, v204
	v_add_u32_e32 v140, s63, v129
	v_ashrrev_i32_e32 v151, 31, v150
	v_ashrrev_i32_e32 v152, 31, v140
	v_lshl_add_u64 v[150:151], v[150:151], 1, s[80:81]
	v_mul_lo_u32 v154, s78, v152
	v_mul_lo_u32 v163, s79, v140
	v_mad_u64_u32 v[152:153], s[80:81], s78, v140, 0
	v_add3_u32 v153, v153, v154, v163
	v_lshl_add_u64 v[152:153], v[152:153], 1, v[150:151]
	v_cvt_pk_bf16_f32 v156, v155, v156
	v_cvt_pk_bf16_f32 v157, v157, v158
	v_cvt_pk_bf16_f32 v158, v159, v160
	v_cvt_pk_bf16_f32 v159, v161, v162
	global_store_dwordx4 v[152:153], v[156:159], off
	s_and_b64 vcc, exec, s[6:7]
	v_mov_b32_e32 v155, v124
	v_mov_b32_e32 v156, v125
	v_mov_b32_e32 v157, v126
	v_mov_b32_e32 v158, v127
	v_mov_b32_e32 v159, v112
	v_mov_b32_e32 v160, v113
	v_mov_b32_e32 v161, v114
	v_mov_b32_e32 v162, v115
	s_cbranch_vccnz .LBB0_141
	v_mul_f32_e32 v156, s60, v124
	v_mul_f32_e32 v157, s60, v125
	v_mul_f32_e32 v158, s60, v126
	v_mul_f32_e32 v159, s60, v127
	v_mul_f32_e32 v160, s60, v112
	v_mul_f32_e32 v161, s60, v113
	v_mul_f32_e32 v162, s60, v114
	v_mul_f32_e32 v163, s60, v115
	v_exp_f32_e32 v156, v156
	v_exp_f32_e32 v157, v157
	v_exp_f32_e32 v158, v158
	v_exp_f32_e32 v159, v159
	v_exp_f32_e32 v160, v160
	v_exp_f32_e32 v161, v161
	v_exp_f32_e32 v162, v162
	v_exp_f32_e32 v163, v163
	v_add_f32_e32 v156, 1.0, v156
	v_add_f32_e32 v157, 1.0, v157
	v_add_f32_e32 v158, 1.0, v158
	v_add_f32_e32 v159, 1.0, v159
	v_add_f32_e32 v160, 1.0, v160
	v_add_f32_e32 v161, 1.0, v161
	v_add_f32_e32 v162, 1.0, v162
	v_add_f32_e32 v163, 1.0, v163
	v_rcp_f32_e32 v155, v156
	v_rcp_f32_e32 v156, v157
	v_rcp_f32_e32 v157, v158
	v_rcp_f32_e32 v158, v159
	v_rcp_f32_e32 v159, v160
	v_rcp_f32_e32 v160, v161
	v_rcp_f32_e32 v161, v162
	v_rcp_f32_e32 v162, v163
.LBB0_141:
	v_cvt_pk_bf16_f32 v156, v155, v156
	v_cvt_pk_bf16_f32 v157, v157, v158
	v_cvt_pk_bf16_f32 v158, v159, v160
	v_cvt_pk_bf16_f32 v159, v161, v162
	global_store_dwordx4 v[152:153], v[156:159], off offset:256
	s_and_b64 vcc, exec, s[6:7]
	v_mov_b32_e32 v155, v104
	v_mov_b32_e32 v156, v105
	v_mov_b32_e32 v157, v106
	v_mov_b32_e32 v158, v107
	v_mov_b32_e32 v159, v100
	v_mov_b32_e32 v160, v101
	v_mov_b32_e32 v161, v102
	v_mov_b32_e32 v162, v103
	s_cbranch_vccnz .LBB0_143
	v_mul_f32_e32 v152, s60, v104
	v_mul_f32_e32 v153, s60, v105
	v_mul_f32_e32 v156, s60, v106
	v_mul_f32_e32 v157, s60, v107
	v_exp_f32_e32 v152, v152
	v_exp_f32_e32 v153, v153
	v_exp_f32_e32 v158, v156
	v_exp_f32_e32 v159, v157
	v_mul_f32_e32 v160, s60, v102
	v_mul_f32_e32 v161, s60, v103
	v_add_f32_e32 v152, 1.0, v152
	v_add_f32_e32 v153, 1.0, v153
	v_exp_f32_e32 v162, v160
	v_rcp_f32_e32 v155, v152
	v_rcp_f32_e32 v156, v153
	v_add_f32_e32 v152, 1.0, v158
	v_add_f32_e32 v153, 1.0, v159
	v_exp_f32_e32 v163, v161
	v_rcp_f32_e32 v157, v152
	v_rcp_f32_e32 v158, v153
	v_mul_f32_e32 v152, s60, v100
	v_mul_f32_e32 v153, s60, v101
	s_nop 0
	v_exp_f32_e32 v152, v152
	v_exp_f32_e32 v153, v153
	s_nop 0
	v_add_f32_e32 v152, 1.0, v152
	v_add_f32_e32 v153, 1.0, v153
	s_nop 0
	v_rcp_f32_e32 v159, v152
	v_rcp_f32_e32 v160, v153
	v_add_f32_e32 v152, 1.0, v162
	v_add_f32_e32 v153, 1.0, v163
	s_nop 0
	v_rcp_f32_e32 v161, v152
	v_rcp_f32_e32 v162, v153
.LBB0_143:
	v_or_b32_e32 v152, 16, v140
	v_mul_lo_u32 v163, s79, v152
	v_mad_u64_u32 v[152:153], s[80:81], s78, v152, 0
	v_add3_u32 v153, v153, v154, v163
	v_lshl_add_u64 v[152:153], v[152:153], 1, v[150:151]
	v_cvt_pk_bf16_f32 v156, v155, v156
	v_cvt_pk_bf16_f32 v157, v157, v158
	v_cvt_pk_bf16_f32 v158, v159, v160
	v_cvt_pk_bf16_f32 v159, v161, v162
	global_store_dwordx4 v[152:153], v[156:159], off
	s_and_b64 vcc, exec, s[6:7]
	v_mov_b32_e32 v155, v108
	v_mov_b32_e32 v156, v109
	v_mov_b32_e32 v157, v110
	v_mov_b32_e32 v158, v111
	v_mov_b32_e32 v159, v96
	v_mov_b32_e32 v160, v97
	v_mov_b32_e32 v161, v98
	v_mov_b32_e32 v162, v99
	s_cbranch_vccnz .LBB0_145
	v_mul_f32_e32 v156, s60, v108
	v_mul_f32_e32 v157, s60, v109
	v_mul_f32_e32 v158, s60, v110
	v_mul_f32_e32 v159, s60, v111
	v_mul_f32_e32 v160, s60, v96
	v_mul_f32_e32 v161, s60, v97
	v_mul_f32_e32 v162, s60, v98
	v_mul_f32_e32 v163, s60, v99
	v_exp_f32_e32 v156, v156
	v_exp_f32_e32 v157, v157
	v_exp_f32_e32 v158, v158
	v_exp_f32_e32 v159, v159
	v_exp_f32_e32 v160, v160
	v_exp_f32_e32 v161, v161
	v_exp_f32_e32 v162, v162
	v_exp_f32_e32 v163, v163
	v_add_f32_e32 v156, 1.0, v156
	v_add_f32_e32 v157, 1.0, v157
	v_add_f32_e32 v158, 1.0, v158
	v_add_f32_e32 v159, 1.0, v159
	v_add_f32_e32 v160, 1.0, v160
	v_add_f32_e32 v161, 1.0, v161
	v_add_f32_e32 v162, 1.0, v162
	v_add_f32_e32 v163, 1.0, v163
	v_rcp_f32_e32 v155, v156
	v_rcp_f32_e32 v156, v157
	v_rcp_f32_e32 v157, v158
	v_rcp_f32_e32 v158, v159
	v_rcp_f32_e32 v159, v160
	v_rcp_f32_e32 v160, v161
	v_rcp_f32_e32 v161, v162
	v_rcp_f32_e32 v162, v163
; __device__ __forceinline__ u32x4 pack8(f32x4 v0, f32x4 v1) { u32x4 w; w.x = cvt_pk_bf16(v0[0], v0[1]); w.y = cvt_pk_bf16(v0[2], v0[3]); w.z = cvt_pk_bf16(v1[0], v1[1]); w.w = cvt_pk_bf16(v1[2], v1[3]); return w; }
; __device__ __forceinline__ f32x4 sigmoid4(f32x4 v) { const f32x2 a = sigmoid2((f32x2){v[0], v[1]}), b = sigmoid2((f32x2){v[2], v[3]}); return (f32x4){a.x, a.y, b.x, b.y}; }
; __device__ __forceinline__ f32x2 sigmoid2(f32x2 x) { const f32x2 t = x * (-LOG2E); f32x2 e; e.x = __builtin_amdgcn_exp2f(t.x); e.y = __builtin_amdgcn_exp2f(t.y);
;     const f32x2 d = e + 1.0f; f32x2 r; r.x = __builtin_amdgcn_rcpf(d.x); r.y = __builtin_amdgcn_rcpf(d.y); return r; }
;     __device__ __forceinline__ void operator()(const f32x4 (&acc)[2][2][4][2], const Unit& u, int ui, int wr, int wc, int fr, int fq) const {
;     ...
;         bf16_t* base; size_t ld; int row0, col0, act;
;         if (pn < 12)      { base = (bf16_t*)(ws + WS_Q);  ld = DM;  row0 = u.pm * 256; col0 = (pn - 8) * 256;  act = 0; }
;         else if (pn < 13) { base = (bf16_t*)(ws + WS_K);  ld = 256; row0 = u.pm * 256; col0 = 0;               act = 0; }
;         else if (pn < 17) { base = (bf16_t*)(ws + WS_SB); ld = DM;  row0 = u.pm * 256; col0 = (pn - 13) * 256; act = 2; }
;         else              { base = (bf16_t*)(ws + WS_VT); ld = MTOK; row0 = 0; col0 = u.pm * 256; act = 0; }
;         const int r0 = row0 + wr * 64 + fr, c0 = col0 + wc * 32 + 8 * fq;
; #pragma unroll
;         for (int ai = 0; ai < 2; ++ai)
; #pragma unroll
;             for (int m = 0; m < 4; ++m) { bf16_t* rowp = base + (size_t)(r0 + ai * 128 + m * 16) * ld + c0;
; #pragma unroll
;                 for (int bj = 0; bj < 2; ++bj) { f32x4 v0 = acc[ai][bj][m][0], v1 = acc[ai][bj][m][1];
;                     if (act == 2) { v0 = sigmoid4(v0); v1 = sigmoid4(v1); }
;                     *(u32x4*)(rowp + bj * 128) = pack8(v0, v1); } }
.LBB0_145:
	v_cvt_pk_bf16_f32 v156, v155, v156
	v_cvt_pk_bf16_f32 v157, v157, v158
	v_cvt_pk_bf16_f32 v158, v159, v160
	v_cvt_pk_bf16_f32 v159, v161, v162
	global_store_dwordx4 v[152:153], v[156:159], off offset:256
	s_and_b64 vcc, exec, s[6:7]
	v_mov_b32_e32 v155, v88
	v_mov_b32_e32 v156, v89
	v_mov_b32_e32 v157, v90
	v_mov_b32_e32 v158, v91
	v_mov_b32_e32 v159, v84
	v_mov_b32_e32 v160, v85
	v_mov_b32_e32 v161, v86
	v_mov_b32_e32 v162, v87
	s_cbranch_vccnz .LBB0_147
	v_mul_f32_e32 v152, s60, v88
	v_mul_f32_e32 v153, s60, v89
	v_mul_f32_e32 v156, s60, v90
	v_mul_f32_e32 v157, s60, v91
	v_exp_f32_e32 v152, v152
	v_exp_f32_e32 v153, v153
	v_exp_f32_e32 v158, v156
	v_exp_f32_e32 v159, v157
	v_mul_f32_e32 v160, s60, v86
	v_mul_f32_e32 v161, s60, v87
	v_add_f32_e32 v152, 1.0, v152
	v_add_f32_e32 v153, 1.0, v153
	v_exp_f32_e32 v162, v160
	v_rcp_f32_e32 v155, v152
	v_rcp_f32_e32 v156, v153
	v_add_f32_e32 v152, 1.0, v158
	v_add_f32_e32 v153, 1.0, v159
	v_exp_f32_e32 v163, v161
	v_rcp_f32_e32 v157, v152
	v_rcp_f32_e32 v158, v153
	v_mul_f32_e32 v152, s60, v84
	v_mul_f32_e32 v153, s60, v85
	s_nop 0
	v_exp_f32_e32 v152, v152
	v_exp_f32_e32 v153, v153
	s_nop 0
	v_add_f32_e32 v152, 1.0, v152
	v_add_f32_e32 v153, 1.0, v153
	s_nop 0
	v_rcp_f32_e32 v159, v152
	v_rcp_f32_e32 v160, v153
	v_add_f32_e32 v152, 1.0, v162
	v_add_f32_e32 v153, 1.0, v163
	s_nop 0
	v_rcp_f32_e32 v161, v152
	v_rcp_f32_e32 v162, v153
.LBB0_147:
	v_or_b32_e32 v152, 32, v140
	v_mul_lo_u32 v163, s79, v152
	v_mad_u64_u32 v[152:153], s[80:81], s78, v152, 0
	v_add3_u32 v153, v153, v154, v163
	v_lshl_add_u64 v[152:153], v[152:153], 1, v[150:151]
	v_cvt_pk_bf16_f32 v156, v155, v156
	v_cvt_pk_bf16_f32 v157, v157, v158
	v_cvt_pk_bf16_f32 v158, v159, v160
	v_cvt_pk_bf16_f32 v159, v161, v162
	global_store_dwordx4 v[152:153], v[156:159], off
	s_and_b64 vcc, exec, s[6:7]
	v_mov_b32_e32 v155, v92
	v_mov_b32_e32 v156, v93
	v_mov_b32_e32 v157, v94
	v_mov_b32_e32 v158, v95
	v_mov_b32_e32 v159, v80
	v_mov_b32_e32 v160, v81
	v_mov_b32_e32 v161, v82
	v_mov_b32_e32 v162, v83
	s_cbranch_vccnz .LBB0_149
	v_mul_f32_e32 v156, s60, v92
	v_mul_f32_e32 v157, s60, v93
	v_mul_f32_e32 v158, s60, v94
	v_mul_f32_e32 v159, s60, v95
	v_mul_f32_e32 v160, s60, v80
	v_mul_f32_e32 v161, s60, v81
	v_mul_f32_e32 v162, s60, v82
	v_mul_f32_e32 v163, s60, v83
	v_exp_f32_e32 v156, v156
	v_exp_f32_e32 v157, v157
	v_exp_f32_e32 v158, v158
	v_exp_f32_e32 v159, v159
	v_exp_f32_e32 v160, v160
	v_exp_f32_e32 v161, v161
	v_exp_f32_e32 v162, v162
	v_exp_f32_e32 v163, v163
	v_add_f32_e32 v156, 1.0, v156
	v_add_f32_e32 v157, 1.0, v157
	v_add_f32_e32 v158, 1.0, v158
	v_add_f32_e32 v159, 1.0, v159
	v_add_f32_e32 v160, 1.0, v160
	v_add_f32_e32 v161, 1.0, v161
	v_add_f32_e32 v162, 1.0, v162
	v_add_f32_e32 v163, 1.0, v163
	v_rcp_f32_e32 v155, v156
	v_rcp_f32_e32 v156, v157
	v_rcp_f32_e32 v157, v158
	v_rcp_f32_e32 v158, v159
	v_rcp_f32_e32 v159, v160
	v_rcp_f32_e32 v160, v161
	v_rcp_f32_e32 v161, v162
	v_rcp_f32_e32 v162, v163
.LBB0_149:
	v_cvt_pk_bf16_f32 v156, v155, v156
	v_cvt_pk_bf16_f32 v157, v157, v158
	v_cvt_pk_bf16_f32 v158, v159, v160
	v_cvt_pk_bf16_f32 v159, v161, v162
	global_store_dwordx4 v[152:153], v[156:159], off offset:256
	s_and_b64 vcc, exec, s[6:7]
	v_mov_b32_e32 v155, v72
	v_mov_b32_e32 v156, v73
	v_mov_b32_e32 v157, v74
	v_mov_b32_e32 v158, v75
	v_mov_b32_e32 v159, v68
	v_mov_b32_e32 v160, v69
	v_mov_b32_e32 v161, v70
	v_mov_b32_e32 v162, v71
	s_cbranch_vccnz .LBB0_151
	v_mul_f32_e32 v152, s60, v72
	v_mul_f32_e32 v153, s60, v73
	v_mul_f32_e32 v156, s60, v74
	v_mul_f32_e32 v157, s60, v75
	v_exp_f32_e32 v152, v152
	v_exp_f32_e32 v153, v153
	v_exp_f32_e32 v158, v156
	v_exp_f32_e32 v159, v157
	v_mul_f32_e32 v160, s60, v70
	v_mul_f32_e32 v161, s60, v71
	v_add_f32_e32 v152, 1.0, v152
	v_add_f32_e32 v153, 1.0, v153
	v_exp_f32_e32 v162, v160
	v_rcp_f32_e32 v155, v152
	v_rcp_f32_e32 v156, v153
	v_add_f32_e32 v152, 1.0, v158
	v_add_f32_e32 v153, 1.0, v159
	v_exp_f32_e32 v163, v161
	v_rcp_f32_e32 v157, v152
	v_rcp_f32_e32 v158, v153
	v_mul_f32_e32 v152, s60, v68
	v_mul_f32_e32 v153, s60, v69
	s_nop 0
	v_exp_f32_e32 v152, v152
	v_exp_f32_e32 v153, v153
	s_nop 0
	v_add_f32_e32 v152, 1.0, v152
	v_add_f32_e32 v153, 1.0, v153
	s_nop 0
	v_rcp_f32_e32 v159, v152
	v_rcp_f32_e32 v160, v153
	v_add_f32_e32 v152, 1.0, v162
	v_add_f32_e32 v153, 1.0, v163
	s_nop 0
	v_rcp_f32_e32 v161, v152
	v_rcp_f32_e32 v162, v153
.LBB0_151:
	v_or_b32_e32 v152, 48, v140
	v_mul_lo_u32 v163, s79, v152
	v_mad_u64_u32 v[152:153], s[80:81], s78, v152, 0
	v_add3_u32 v153, v153, v154, v163
	v_lshl_add_u64 v[152:153], v[152:153], 1, v[150:151]
	v_cvt_pk_bf16_f32 v154, v155, v156
	v_cvt_pk_bf16_f32 v155, v157, v158
	v_cvt_pk_bf16_f32 v156, v159, v160
	v_cvt_pk_bf16_f32 v157, v161, v162
	global_store_dwordx4 v[152:153], v[154:157], off
	s_and_b64 vcc, exec, s[6:7]
	v_mov_b32_e32 v158, v64
	v_mov_b32_e32 v154, v76
	v_mov_b32_e32 v155, v77
	v_mov_b32_e32 v156, v78
	v_mov_b32_e32 v157, v79
	v_mov_b32_e32 v159, v65
	v_mov_b32_e32 v160, v66
	v_mov_b32_e32 v161, v67
	s_cbranch_vccnz .LBB0_153
	v_mul_f32_e32 v154, s60, v76
	v_mul_f32_e32 v155, s60, v77
	v_mul_f32_e32 v156, s60, v78
	v_mul_f32_e32 v157, s60, v79
	v_mul_f32_e32 v158, s60, v64
	v_mul_f32_e32 v159, s60, v65
	v_mul_f32_e32 v160, s60, v66
	v_mul_f32_e32 v161, s60, v67
	v_exp_f32_e32 v154, v154
	v_exp_f32_e32 v155, v155
	v_exp_f32_e32 v156, v156
	v_exp_f32_e32 v157, v157
	v_exp_f32_e32 v158, v158
	v_exp_f32_e32 v159, v159
	v_exp_f32_e32 v160, v160
	v_exp_f32_e32 v161, v161
	v_add_f32_e32 v154, 1.0, v154
	v_add_f32_e32 v155, 1.0, v155
	v_add_f32_e32 v156, 1.0, v156
	v_add_f32_e32 v157, 1.0, v157
	v_add_f32_e32 v158, 1.0, v158
	v_add_f32_e32 v159, 1.0, v159
	v_add_f32_e32 v160, 1.0, v160
	v_add_f32_e32 v161, 1.0, v161
	v_rcp_f32_e32 v154, v154
	v_rcp_f32_e32 v155, v155
	v_rcp_f32_e32 v156, v156
	v_rcp_f32_e32 v157, v157
	v_rcp_f32_e32 v158, v158
	v_rcp_f32_e32 v159, v159
	v_rcp_f32_e32 v160, v160
	v_rcp_f32_e32 v161, v161
; __device__ __forceinline__ u32x4 pack8(f32x4 v0, f32x4 v1) { u32x4 w; w.x = cvt_pk_bf16(v0[0], v0[1]); w.y = cvt_pk_bf16(v0[2], v0[3]); w.z = cvt_pk_bf16(v1[0], v1[1]); w.w = cvt_pk_bf16(v1[2], v1[3]); return w; }
; __device__ __forceinline__ f32x4 sigmoid4(f32x4 v) { const f32x2 a = sigmoid2((f32x2){v[0], v[1]}), b = sigmoid2((f32x2){v[2], v[3]}); return (f32x4){a.x, a.y, b.x, b.y}; }
; __device__ __forceinline__ f32x2 sigmoid2(f32x2 x) { const f32x2 t = x * (-LOG2E); f32x2 e; e.x = __builtin_amdgcn_exp2f(t.x); e.y = __builtin_amdgcn_exp2f(t.y);
;     const f32x2 d = e + 1.0f; f32x2 r; r.x = __builtin_amdgcn_rcpf(d.x); r.y = __builtin_amdgcn_rcpf(d.y); return r; }
;     __device__ __forceinline__ void operator()(const f32x4 (&acc)[2][2][4][2], const Unit& u, int ui, int wr, int wc, int fr, int fq) const {
;     ...
;         bf16_t* base; size_t ld; int row0, col0, act;
;         if (pn < 12)      { base = (bf16_t*)(ws + WS_Q);  ld = DM;  row0 = u.pm * 256; col0 = (pn - 8) * 256;  act = 0; }
;         else if (pn < 13) { base = (bf16_t*)(ws + WS_K);  ld = 256; row0 = u.pm * 256; col0 = 0;               act = 0; }
;         else if (pn < 17) { base = (bf16_t*)(ws + WS_SB); ld = DM;  row0 = u.pm * 256; col0 = (pn - 13) * 256; act = 2; }
;         else              { base = (bf16_t*)(ws + WS_VT); ld = MTOK; row0 = 0; col0 = u.pm * 256; act = 0; }
;         const int r0 = row0 + wr * 64 + fr, c0 = col0 + wc * 32 + 8 * fq;
; #pragma unroll
;         for (int ai = 0; ai < 2; ++ai)
; #pragma unroll
;             for (int m = 0; m < 4; ++m) { bf16_t* rowp = base + (size_t)(r0 + ai * 128 + m * 16) * ld + c0;
; #pragma unroll
;                 for (int bj = 0; bj < 2; ++bj) { f32x4 v0 = acc[ai][bj][m][0], v1 = acc[ai][bj][m][1];
;                     if (act == 2) { v0 = sigmoid4(v0); v1 = sigmoid4(v1); }
;                     *(u32x4*)(rowp + bj * 128) = pack8(v0, v1); } }
.LBB0_153:
	v_cvt_pk_bf16_f32 v154, v154, v155
	v_cvt_pk_bf16_f32 v155, v156, v157
	v_cvt_pk_bf16_f32 v156, v158, v159
	v_cvt_pk_bf16_f32 v157, v160, v161
	global_store_dwordx4 v[152:153], v[154:157], off offset:256
	s_and_b64 vcc, exec, s[6:7]
	v_mov_b32_e32 v158, v52
	v_mov_b32_e32 v154, v56
	v_mov_b32_e32 v155, v57
	v_mov_b32_e32 v156, v58
	v_mov_b32_e32 v157, v59
	v_mov_b32_e32 v159, v53
	v_mov_b32_e32 v160, v54
	v_mov_b32_e32 v161, v55
	s_cbranch_vccnz .LBB0_155
	v_mul_f32_e32 v152, s60, v56
	v_mul_f32_e32 v153, s60, v57
	v_mul_f32_e32 v154, s60, v58
	v_mul_f32_e32 v155, s60, v59
	v_exp_f32_e32 v152, v152
	v_exp_f32_e32 v153, v153
	v_exp_f32_e32 v156, v154
	v_exp_f32_e32 v157, v155
	v_mul_f32_e32 v158, s60, v54
	v_mul_f32_e32 v159, s60, v55
	v_add_f32_e32 v152, 1.0, v152
	v_add_f32_e32 v153, 1.0, v153
	v_exp_f32_e32 v160, v158
	v_rcp_f32_e32 v154, v152
	v_rcp_f32_e32 v155, v153
	v_add_f32_e32 v152, 1.0, v156
	v_add_f32_e32 v153, 1.0, v157
	v_exp_f32_e32 v161, v159
	v_rcp_f32_e32 v156, v152
	v_rcp_f32_e32 v157, v153
	v_mul_f32_e32 v152, s60, v52
	v_mul_f32_e32 v153, s60, v53
	s_nop 0
	v_exp_f32_e32 v152, v152
	v_exp_f32_e32 v153, v153
	s_nop 0
	v_add_f32_e32 v152, 1.0, v152
	v_add_f32_e32 v153, 1.0, v153
	s_nop 0
	v_rcp_f32_e32 v158, v152
	v_rcp_f32_e32 v159, v153
	v_add_f32_e32 v152, 1.0, v160
	v_add_f32_e32 v153, 1.0, v161
	s_nop 0
	v_rcp_f32_e32 v160, v152
	v_rcp_f32_e32 v161, v153
.LBB0_155:
	v_add_u32_e32 v152, 0x80, v140
	v_ashrrev_i32_e32 v153, 31, v152
	v_mul_lo_u32 v162, s78, v153
	v_mul_lo_u32 v163, s79, v152
	v_mad_u64_u32 v[152:153], s[80:81], s78, v152, 0
	v_add3_u32 v153, v153, v162, v163
	v_lshl_add_u64 v[152:153], v[152:153], 1, v[150:151]
	v_cvt_pk_bf16_f32 v154, v154, v155
	v_cvt_pk_bf16_f32 v155, v156, v157
	v_cvt_pk_bf16_f32 v156, v158, v159
	v_cvt_pk_bf16_f32 v157, v160, v161
	global_store_dwordx4 v[152:153], v[154:157], off
	s_and_b64 vcc, exec, s[6:7]
	v_mov_b32_e32 v158, v48
	v_mov_b32_e32 v154, v60
	v_mov_b32_e32 v155, v61
	v_mov_b32_e32 v156, v62
	v_mov_b32_e32 v157, v63
	v_mov_b32_e32 v159, v49
	v_mov_b32_e32 v160, v50
	v_mov_b32_e32 v161, v51
	s_cbranch_vccnz .LBB0_157
	v_mul_f32_e32 v154, s60, v60
	v_mul_f32_e32 v155, s60, v61
	v_mul_f32_e32 v156, s60, v62
	v_mul_f32_e32 v157, s60, v63
	v_mul_f32_e32 v158, s60, v48
	v_mul_f32_e32 v159, s60, v49
	v_mul_f32_e32 v160, s60, v50
	v_mul_f32_e32 v161, s60, v51
	v_exp_f32_e32 v154, v154
	v_exp_f32_e32 v155, v155
	v_exp_f32_e32 v156, v156
	v_exp_f32_e32 v157, v157
	v_exp_f32_e32 v158, v158
	v_exp_f32_e32 v159, v159
	v_exp_f32_e32 v160, v160
	v_exp_f32_e32 v161, v161
	v_add_f32_e32 v154, 1.0, v154
	v_add_f32_e32 v155, 1.0, v155
	v_add_f32_e32 v156, 1.0, v156
	v_add_f32_e32 v157, 1.0, v157
	v_add_f32_e32 v158, 1.0, v158
	v_add_f32_e32 v159, 1.0, v159
	v_add_f32_e32 v160, 1.0, v160
	v_add_f32_e32 v161, 1.0, v161
	v_rcp_f32_e32 v154, v154
	v_rcp_f32_e32 v155, v155
	v_rcp_f32_e32 v156, v156
	v_rcp_f32_e32 v157, v157
	v_rcp_f32_e32 v158, v158
	v_rcp_f32_e32 v159, v159
	v_rcp_f32_e32 v160, v160
	v_rcp_f32_e32 v161, v161
.LBB0_157:
	v_cvt_pk_bf16_f32 v154, v154, v155
	v_cvt_pk_bf16_f32 v155, v156, v157
	v_cvt_pk_bf16_f32 v156, v158, v159
	v_cvt_pk_bf16_f32 v157, v160, v161
	global_store_dwordx4 v[152:153], v[154:157], off offset:256
	s_and_b64 vcc, exec, s[6:7]
	v_mov_b32_e32 v158, v36
	v_mov_b32_e32 v154, v40
	v_mov_b32_e32 v155, v41
	v_mov_b32_e32 v156, v42
	v_mov_b32_e32 v157, v43
	v_mov_b32_e32 v159, v37
	v_mov_b32_e32 v160, v38
	v_mov_b32_e32 v161, v39
	s_cbranch_vccnz .LBB0_159
	v_mul_f32_e32 v152, s60, v40
	v_mul_f32_e32 v153, s60, v41
	v_mul_f32_e32 v154, s60, v42
	v_mul_f32_e32 v155, s60, v43
	v_exp_f32_e32 v152, v152
	v_exp_f32_e32 v153, v153
	v_exp_f32_e32 v156, v154
	v_exp_f32_e32 v157, v155
	v_mul_f32_e32 v158, s60, v38
	v_mul_f32_e32 v159, s60, v39
	v_add_f32_e32 v152, 1.0, v152
	v_add_f32_e32 v153, 1.0, v153
	v_exp_f32_e32 v160, v158
	v_rcp_f32_e32 v154, v152
	v_rcp_f32_e32 v155, v153
	v_add_f32_e32 v152, 1.0, v156
	v_add_f32_e32 v153, 1.0, v157
	v_exp_f32_e32 v161, v159
	v_rcp_f32_e32 v156, v152
	v_rcp_f32_e32 v157, v153
	v_mul_f32_e32 v152, s60, v36
	v_mul_f32_e32 v153, s60, v37
	s_nop 0
	v_exp_f32_e32 v152, v152
	v_exp_f32_e32 v153, v153
	s_nop 0
	v_add_f32_e32 v152, 1.0, v152
	v_add_f32_e32 v153, 1.0, v153
	s_nop 0
	v_rcp_f32_e32 v158, v152
	v_rcp_f32_e32 v159, v153
	v_add_f32_e32 v152, 1.0, v160
	v_add_f32_e32 v153, 1.0, v161
	s_nop 0
	v_rcp_f32_e32 v160, v152
	v_rcp_f32_e32 v161, v153
.LBB0_159:
	v_add_u32_e32 v152, 0x90, v140
	v_ashrrev_i32_e32 v153, 31, v152
	v_mul_lo_u32 v162, s78, v153
	v_mul_lo_u32 v163, s79, v152
	v_mad_u64_u32 v[152:153], s[80:81], s78, v152, 0
	v_add3_u32 v153, v153, v162, v163
	v_lshl_add_u64 v[152:153], v[152:153], 1, v[150:151]
	v_cvt_pk_bf16_f32 v154, v154, v155
	v_cvt_pk_bf16_f32 v155, v156, v157
	v_cvt_pk_bf16_f32 v156, v158, v159
	v_cvt_pk_bf16_f32 v157, v160, v161
	global_store_dwordx4 v[152:153], v[154:157], off
	s_and_b64 vcc, exec, s[6:7]
	v_mov_b32_e32 v158, v32
	v_mov_b32_e32 v154, v44
	v_mov_b32_e32 v155, v45
	v_mov_b32_e32 v156, v46
	v_mov_b32_e32 v157, v47
	v_mov_b32_e32 v159, v33
	v_mov_b32_e32 v160, v34
	v_mov_b32_e32 v161, v35
	s_cbranch_vccnz .LBB0_161
	v_mul_f32_e32 v154, s60, v44
	v_mul_f32_e32 v155, s60, v45
	v_mul_f32_e32 v156, s60, v46
	v_mul_f32_e32 v157, s60, v47
	v_mul_f32_e32 v158, s60, v32
	v_mul_f32_e32 v159, s60, v33
	v_mul_f32_e32 v160, s60, v34
	v_mul_f32_e32 v161, s60, v35
	v_exp_f32_e32 v154, v154
	v_exp_f32_e32 v155, v155
	v_exp_f32_e32 v156, v156
	v_exp_f32_e32 v157, v157
	v_exp_f32_e32 v158, v158
	v_exp_f32_e32 v159, v159
	v_exp_f32_e32 v160, v160
	v_exp_f32_e32 v161, v161
	v_add_f32_e32 v154, 1.0, v154
	v_add_f32_e32 v155, 1.0, v155
	v_add_f32_e32 v156, 1.0, v156
	v_add_f32_e32 v157, 1.0, v157
	v_add_f32_e32 v158, 1.0, v158
	v_add_f32_e32 v159, 1.0, v159
	v_add_f32_e32 v160, 1.0, v160
	v_add_f32_e32 v161, 1.0, v161
	v_rcp_f32_e32 v154, v154
	v_rcp_f32_e32 v155, v155
	v_rcp_f32_e32 v156, v156
	v_rcp_f32_e32 v157, v157
	v_rcp_f32_e32 v158, v158
	v_rcp_f32_e32 v159, v159
	v_rcp_f32_e32 v160, v160
	v_rcp_f32_e32 v161, v161
; __device__ __forceinline__ u32x4 pack8(f32x4 v0, f32x4 v1) { u32x4 w; w.x = cvt_pk_bf16(v0[0], v0[1]); w.y = cvt_pk_bf16(v0[2], v0[3]); w.z = cvt_pk_bf16(v1[0], v1[1]); w.w = cvt_pk_bf16(v1[2], v1[3]); return w; }
; __device__ __forceinline__ f32x4 sigmoid4(f32x4 v) { const f32x2 a = sigmoid2((f32x2){v[0], v[1]}), b = sigmoid2((f32x2){v[2], v[3]}); return (f32x4){a.x, a.y, b.x, b.y}; }
; __device__ __forceinline__ f32x2 sigmoid2(f32x2 x) { const f32x2 t = x * (-LOG2E); f32x2 e; e.x = __builtin_amdgcn_exp2f(t.x); e.y = __builtin_amdgcn_exp2f(t.y);
;     const f32x2 d = e + 1.0f; f32x2 r; r.x = __builtin_amdgcn_rcpf(d.x); r.y = __builtin_amdgcn_rcpf(d.y); return r; }
;     __device__ __forceinline__ void operator()(const f32x4 (&acc)[2][2][4][2], const Unit& u, int ui, int wr, int wc, int fr, int fq) const {
;     ...
;         bf16_t* base; size_t ld; int row0, col0, act;
;         if (pn < 12)      { base = (bf16_t*)(ws + WS_Q);  ld = DM;  row0 = u.pm * 256; col0 = (pn - 8) * 256;  act = 0; }
;         else if (pn < 13) { base = (bf16_t*)(ws + WS_K);  ld = 256; row0 = u.pm * 256; col0 = 0;               act = 0; }
;         else if (pn < 17) { base = (bf16_t*)(ws + WS_SB); ld = DM;  row0 = u.pm * 256; col0 = (pn - 13) * 256; act = 2; }
;         else              { base = (bf16_t*)(ws + WS_VT); ld = MTOK; row0 = 0; col0 = u.pm * 256; act = 0; }
;         const int r0 = row0 + wr * 64 + fr, c0 = col0 + wc * 32 + 8 * fq;
; #pragma unroll
;         for (int ai = 0; ai < 2; ++ai)
; #pragma unroll
;             for (int m = 0; m < 4; ++m) { bf16_t* rowp = base + (size_t)(r0 + ai * 128 + m * 16) * ld + c0;
; #pragma unroll
;                 for (int bj = 0; bj < 2; ++bj) { f32x4 v0 = acc[ai][bj][m][0], v1 = acc[ai][bj][m][1];
;                     if (act == 2) { v0 = sigmoid4(v0); v1 = sigmoid4(v1); }
;                     *(u32x4*)(rowp + bj * 128) = pack8(v0, v1); } }
.LBB0_161:
	v_cvt_pk_bf16_f32 v154, v154, v155
	v_cvt_pk_bf16_f32 v155, v156, v157
	v_cvt_pk_bf16_f32 v156, v158, v159
	v_cvt_pk_bf16_f32 v157, v160, v161
	global_store_dwordx4 v[152:153], v[154:157], off offset:256
	s_and_b64 vcc, exec, s[6:7]
	v_mov_b32_e32 v158, v20
	v_mov_b32_e32 v154, v24
	v_mov_b32_e32 v155, v25
	v_mov_b32_e32 v156, v26
	v_mov_b32_e32 v157, v27
	v_mov_b32_e32 v159, v21
	v_mov_b32_e32 v160, v22
	v_mov_b32_e32 v161, v23
	s_cbranch_vccnz .LBB0_163
	v_mul_f32_e32 v152, s60, v24
	v_mul_f32_e32 v153, s60, v25
	v_mul_f32_e32 v154, s60, v26
	v_mul_f32_e32 v155, s60, v27
	v_exp_f32_e32 v152, v152
	v_exp_f32_e32 v153, v153
	v_exp_f32_e32 v156, v154
	v_exp_f32_e32 v157, v155
	v_mul_f32_e32 v158, s60, v22
	v_mul_f32_e32 v159, s60, v23
	v_add_f32_e32 v152, 1.0, v152
	v_add_f32_e32 v153, 1.0, v153
	v_exp_f32_e32 v160, v158
	v_rcp_f32_e32 v154, v152
	v_rcp_f32_e32 v155, v153
	v_add_f32_e32 v152, 1.0, v156
	v_add_f32_e32 v153, 1.0, v157
	v_exp_f32_e32 v161, v159
	v_rcp_f32_e32 v156, v152
	v_rcp_f32_e32 v157, v153
	v_mul_f32_e32 v152, s60, v20
	v_mul_f32_e32 v153, s60, v21
	s_nop 0
	v_exp_f32_e32 v152, v152
	v_exp_f32_e32 v153, v153
	s_nop 0
	v_add_f32_e32 v152, 1.0, v152
	v_add_f32_e32 v153, 1.0, v153
	s_nop 0
	v_rcp_f32_e32 v158, v152
	v_rcp_f32_e32 v159, v153
	v_add_f32_e32 v152, 1.0, v160
	v_add_f32_e32 v153, 1.0, v161
	s_nop 0
	v_rcp_f32_e32 v160, v152
	v_rcp_f32_e32 v161, v153
.LBB0_163:
	v_add_u32_e32 v152, 0xa0, v140
	v_ashrrev_i32_e32 v153, 31, v152
	v_mul_lo_u32 v162, s78, v153
	v_mul_lo_u32 v163, s79, v152
	v_mad_u64_u32 v[152:153], s[80:81], s78, v152, 0
	v_add3_u32 v153, v153, v162, v163
	v_lshl_add_u64 v[152:153], v[152:153], 1, v[150:151]
	v_cvt_pk_bf16_f32 v154, v154, v155
	v_cvt_pk_bf16_f32 v155, v156, v157
	v_cvt_pk_bf16_f32 v156, v158, v159
	v_cvt_pk_bf16_f32 v157, v160, v161
	global_store_dwordx4 v[152:153], v[154:157], off
	s_and_b64 vcc, exec, s[6:7]
	v_mov_b32_e32 v158, v16
	v_mov_b32_e32 v154, v28
	v_mov_b32_e32 v155, v29
	v_mov_b32_e32 v156, v30
	v_mov_b32_e32 v157, v31
	v_mov_b32_e32 v159, v17
	v_mov_b32_e32 v160, v18
	v_mov_b32_e32 v161, v19
	s_cbranch_vccnz .LBB0_165
	v_mul_f32_e32 v154, s60, v28
	v_mul_f32_e32 v155, s60, v29
	v_mul_f32_e32 v156, s60, v30
	v_mul_f32_e32 v157, s60, v31
	v_mul_f32_e32 v158, s60, v16
	v_mul_f32_e32 v159, s60, v17
	v_mul_f32_e32 v160, s60, v18
	v_mul_f32_e32 v161, s60, v19
	v_exp_f32_e32 v154, v154
	v_exp_f32_e32 v155, v155
	v_exp_f32_e32 v156, v156
	v_exp_f32_e32 v157, v157
	v_exp_f32_e32 v158, v158
	v_exp_f32_e32 v159, v159
	v_exp_f32_e32 v160, v160
	v_exp_f32_e32 v161, v161
	v_add_f32_e32 v154, 1.0, v154
	v_add_f32_e32 v155, 1.0, v155
	v_add_f32_e32 v156, 1.0, v156
	v_add_f32_e32 v157, 1.0, v157
	v_add_f32_e32 v158, 1.0, v158
	v_add_f32_e32 v159, 1.0, v159
	v_add_f32_e32 v160, 1.0, v160
	v_add_f32_e32 v161, 1.0, v161
	v_rcp_f32_e32 v154, v154
	v_rcp_f32_e32 v155, v155
	v_rcp_f32_e32 v156, v156
	v_rcp_f32_e32 v157, v157
	v_rcp_f32_e32 v158, v158
	v_rcp_f32_e32 v159, v159
	v_rcp_f32_e32 v160, v160
	v_rcp_f32_e32 v161, v161
.LBB0_165:
	v_cvt_pk_bf16_f32 v154, v154, v155
	v_cvt_pk_bf16_f32 v155, v156, v157
	v_cvt_pk_bf16_f32 v156, v158, v159
	v_cvt_pk_bf16_f32 v157, v160, v161
	global_store_dwordx4 v[152:153], v[154:157], off offset:256
	s_and_b64 vcc, exec, s[6:7]
	v_mov_b32_e32 v152, v8
	v_mov_b32_e32 v153, v9
	v_mov_b32_e32 v154, v10
	v_mov_b32_e32 v155, v11
	v_mov_b32_e32 v156, v4
	v_mov_b32_e32 v157, v5
	v_mov_b32_e32 v158, v6
	v_mov_b32_e32 v159, v7
	s_cbranch_vccnz .LBB0_167
	v_mul_f32_e32 v152, s60, v8
	v_mul_f32_e32 v153, s60, v9
	v_mul_f32_e32 v154, s60, v10
	v_mul_f32_e32 v155, s60, v11
	v_mul_f32_e32 v156, s60, v4
	v_mul_f32_e32 v157, s60, v5
	v_mul_f32_e32 v158, s60, v6
	v_mul_f32_e32 v159, s60, v7
	v_exp_f32_e32 v152, v152
	v_exp_f32_e32 v153, v153
	v_exp_f32_e32 v154, v154
	v_exp_f32_e32 v155, v155
	v_exp_f32_e32 v156, v156
	v_exp_f32_e32 v157, v157
	v_exp_f32_e32 v158, v158
	v_exp_f32_e32 v159, v159
	v_add_f32_e32 v152, 1.0, v152
	v_add_f32_e32 v153, 1.0, v153
	v_add_f32_e32 v154, 1.0, v154
	v_add_f32_e32 v155, 1.0, v155
	v_add_f32_e32 v156, 1.0, v156
	v_add_f32_e32 v157, 1.0, v157
	v_add_f32_e32 v158, 1.0, v158
	v_add_f32_e32 v159, 1.0, v159
	v_rcp_f32_e32 v152, v152
	v_rcp_f32_e32 v153, v153
	v_rcp_f32_e32 v154, v154
	v_rcp_f32_e32 v155, v155
	v_rcp_f32_e32 v156, v156
	v_rcp_f32_e32 v157, v157
	v_rcp_f32_e32 v158, v158
	v_rcp_f32_e32 v159, v159
.LBB0_167:
	v_add_u32_e32 v140, 0xb0, v140
	v_ashrrev_i32_e32 v160, 31, v140
	v_mul_lo_u32 v162, s78, v160
	v_mul_lo_u32 v163, s79, v140
	v_mad_u64_u32 v[160:161], s[78:79], s78, v140, 0
	v_add3_u32 v161, v161, v162, v163
	v_lshl_add_u64 v[150:151], v[160:161], 1, v[150:151]
	v_cvt_pk_bf16_f32 v152, v152, v153
	v_cvt_pk_bf16_f32 v153, v154, v155
	v_cvt_pk_bf16_f32 v154, v156, v157
	v_cvt_pk_bf16_f32 v155, v158, v159
	global_store_dwordx4 v[150:151], v[152:155], off
	s_and_b64 vcc, exec, s[6:7]
	v_mov_b32_e32 v140, v12
	v_mov_b32_e32 v152, v13
	v_mov_b32_e32 v153, v14
	v_mov_b32_e32 v154, v15
	v_mov_b32_e32 v155, v0
	v_mov_b32_e32 v156, v1
	v_mov_b32_e32 v157, v2
	v_mov_b32_e32 v158, v3
	s_cbranch_vccnz .LBB0_169
	v_mul_f32_e32 v152, s60, v12
	v_mul_f32_e32 v153, s60, v13
	v_mul_f32_e32 v154, s60, v14
	v_mul_f32_e32 v155, s60, v15
	v_mul_f32_e32 v156, s60, v0
	v_mul_f32_e32 v157, s60, v1
	v_mul_f32_e32 v158, s60, v2
	v_mul_f32_e32 v159, s60, v3
	v_exp_f32_e32 v152, v152
	v_exp_f32_e32 v153, v153
	v_exp_f32_e32 v154, v154
	v_exp_f32_e32 v155, v155
	v_exp_f32_e32 v156, v156
	v_exp_f32_e32 v157, v157
	v_exp_f32_e32 v158, v158
	v_exp_f32_e32 v159, v159
	v_add_f32_e32 v152, 1.0, v152
	v_add_f32_e32 v153, 1.0, v153
	v_add_f32_e32 v154, 1.0, v154
	v_add_f32_e32 v155, 1.0, v155
	v_add_f32_e32 v156, 1.0, v156
	v_add_f32_e32 v157, 1.0, v157
	v_add_f32_e32 v158, 1.0, v158
	v_add_f32_e32 v159, 1.0, v159
	v_rcp_f32_e32 v140, v152
	v_rcp_f32_e32 v152, v153
	v_rcp_f32_e32 v153, v154
	v_rcp_f32_e32 v154, v155
	v_rcp_f32_e32 v155, v156
	v_rcp_f32_e32 v156, v157
	v_rcp_f32_e32 v157, v158
	v_rcp_f32_e32 v158, v159

; __device__ __forceinline__ u32x4 pack8(f32x4 v0, f32x4 v1) { u32x4 w; w.x = cvt_pk_bf16(v0[0], v0[1]); w.y = cvt_pk_bf16(v0[2], v0[3]); w.z = cvt_pk_bf16(v1[0], v1[1]); w.w = cvt_pk_bf16(v1[2], v1[3]); return w; }
; __device__ __forceinline__ f32x4 gelu4(f32x4 v) { const f32x2 a = gelu2((f32x2){v[0], v[1]}), b = gelu2((f32x2){v[2], v[3]}); return (f32x4){a.x, a.y, b.x, b.y}; }
; __device__ __forceinline__ f32x2 gelu2(f32x2 x) { const f32x2 u = x * x, p = u * (0.044715f * -2.302208198f) + (-2.302208198f), t = x * p; f32x2 e; e.x = __builtin_amdgcn_exp2f(t.x); e.y = __builtin_amdgcn_exp2f(t.y);
;     const f32x2 d = e + 1.0f; f32x2 r; r.x = __builtin_amdgcn_rcpf(d.x); r.y = __builtin_amdgcn_rcpf(d.y); return x * r; }
;     __device__ __forceinline__ void operator()(const f32x4 (&acc)[2][2][4][2], const Unit& u, int ui, int wr, int wc, int fr, int fq) const {
;     ...
;                     for (int m = 0; m < 4; ++m) { const f32x4 g0 = gelu4(acc[ai][bj][m][0]), g1 = gelu4(acc[ai][bj][m][1]);
;                         sq0 += g0 * g0; sq1 += g1 * g1;
;                         *(u32x4*)(base + (size_t)(ai * 128 + m * 16) * MTOK + bj * 128) = pack8(g0, g1); }
.LBB0_170:
	s_and_b64 vcc, exec, s[6:7]
	s_cbranch_vccz .LBB0_190
	v_mul_f32_e32 v154, v122, v122
	v_mul_f32_e32 v155, v123, v123
	v_mul_f32_e32 v156, v120, v120
	v_mul_f32_e32 v157, v121, v121
	v_mov_b64_e32 v[166:167], s[66:67]
	v_mul_f32_e32 v158, v118, v118
	v_mul_f32_e32 v159, v119, v119
	v_mul_f32_e32 v160, v116, v116
	v_mul_f32_e32 v161, v117, v117
	v_fma_f32 v156, -v156, s64, v166
	v_fma_f32 v157, -v157, s64, v166
	v_fma_f32 v154, -v154, s64, v166
	v_fma_f32 v155, -v155, s64, v166
	v_fma_f32 v160, -v160, s64, v166
	v_fma_f32 v161, -v161, s64, v166
	v_fma_f32 v158, -v158, s64, v166
	v_fma_f32 v159, -v159, s64, v166
	v_mul_f32_e32 v156, v120, v156
	v_mul_f32_e32 v157, v121, v157
	v_mul_f32_e32 v154, v122, v154
	v_mul_f32_e32 v155, v123, v155
	v_mul_f32_e32 v160, v116, v160
	v_mul_f32_e32 v161, v117, v161
	v_mul_f32_e32 v158, v118, v158
	v_mul_f32_e32 v159, v119, v159
	v_exp_f32_e32 v156, v156
	v_exp_f32_e32 v157, v157
	v_exp_f32_e32 v154, v154
	v_exp_f32_e32 v155, v155
	v_exp_f32_e32 v160, v160
	v_exp_f32_e32 v161, v161
	v_exp_f32_e32 v158, v158
	v_exp_f32_e32 v159, v159
	v_lshl_add_u32 v140, s25, 8, v129
	v_mov_b64_e32 v[150:151], s[48:49]
	s_mov_b32 s6, 0x30000
	v_mad_u64_u32 v[150:151], s[6:7], v140, s6, v[150:151]
	v_add_f32_e32 v156, 1.0, v156
	v_add_f32_e32 v157, 1.0, v157
	v_add_f32_e32 v154, 1.0, v154
	v_add_f32_e32 v155, 1.0, v155
	v_add_f32_e32 v160, 1.0, v160
	v_add_f32_e32 v161, 1.0, v161
	v_add_f32_e32 v158, 1.0, v158
	v_add_f32_e32 v159, 1.0, v159
	s_lshl_b32 s6, s76, 8
	v_rcp_f32_e32 v156, v156
	v_rcp_f32_e32 v157, v157
	v_rcp_f32_e32 v154, v154
	v_rcp_f32_e32 v155, v155
	v_rcp_f32_e32 v160, v160
	v_rcp_f32_e32 v161, v161
	v_rcp_f32_e32 v158, v158
	v_rcp_f32_e32 v159, v159
	s_ashr_i32 s7, s6, 31
	v_lshl_add_u64 v[150:151], s[6:7], 1, v[150:151]
	s_lshl_b32 s20, s88, 1
	v_lshl_add_u64 v[150:151], v[150:151], 0, s[20:21]
	v_lshlrev_b32_e32 v140, 1, v130
	v_lshl_add_u64 v[152:153], v[150:151], 0, v[140:141]
	v_mul_f32_e32 v162, v120, v156
	v_mul_f32_e32 v163, v121, v157
	v_mul_f32_e32 v168, v122, v154
	v_mul_f32_e32 v169, v123, v155
	v_mul_f32_e32 v160, v116, v160
	v_mul_f32_e32 v161, v117, v161
	v_mul_f32_e32 v170, v118, v158
	v_mul_f32_e32 v171, v119, v159
	v_cvt_pk_bf16_f32 v154, v162, v163
	v_cvt_pk_bf16_f32 v155, v168, v169
	v_cvt_pk_bf16_f32 v156, v160, v161
	v_mul_f32_e32 v158, v102, v102
	v_mul_f32_e32 v159, v103, v103
	v_cvt_pk_bf16_f32 v157, v170, v171
	global_store_dwordx4 v[152:153], v[154:157], off
	v_mul_f32_e32 v164, v100, v100
	v_mul_f32_e32 v165, v101, v101
	v_fma_f32 v158, -v158, s64, v166
	v_fma_f32 v159, -v159, s64, v166
	v_mul_f32_e32 v156, v104, v104
	v_mul_f32_e32 v157, v105, v105
	v_mul_f32_e32 v154, v106, v106
	v_mul_f32_e32 v155, v107, v107
	v_fma_f32 v156, -v156, s64, v166
	v_fma_f32 v157, -v157, s64, v166
	v_fma_f32 v154, -v154, s64, v166
	v_fma_f32 v155, -v155, s64, v166
	v_mul_f32_e32 v156, v104, v156
	v_mul_f32_e32 v157, v105, v157
	v_fma_f32 v164, -v164, s64, v166
	v_fma_f32 v165, -v165, s64, v166
	v_exp_f32_e32 v156, v156
	v_exp_f32_e32 v157, v157
	v_mul_f32_e32 v154, v106, v154
	v_mul_f32_e32 v155, v107, v155
	v_mul_f32_e32 v164, v100, v164
	v_mul_f32_e32 v165, v101, v165
	v_mul_f32_e32 v158, v102, v158
	v_mul_f32_e32 v159, v103, v159
	v_exp_f32_e32 v154, v154
	v_exp_f32_e32 v155, v155
	v_exp_f32_e32 v164, v164
	v_exp_f32_e32 v165, v165
	v_exp_f32_e32 v158, v158
	v_exp_f32_e32 v159, v159
	v_add_f32_e32 v156, 1.0, v156
	v_add_f32_e32 v157, 1.0, v157
	v_add_f32_e32 v154, 1.0, v154
	v_add_f32_e32 v155, 1.0, v155
	v_rcp_f32_e32 v156, v156
	v_rcp_f32_e32 v157, v157
	v_add_f32_e32 v164, 1.0, v164
	v_add_f32_e32 v165, 1.0, v165
	v_add_f32_e32 v158, 1.0, v158
	v_add_f32_e32 v159, 1.0, v159
	v_rcp_f32_e32 v154, v154
	v_rcp_f32_e32 v155, v155
	v_rcp_f32_e32 v164, v164
	v_rcp_f32_e32 v165, v165
	v_rcp_f32_e32 v158, v158
	v_rcp_f32_e32 v159, v159
	v_mul_f32_e32 v156, v104, v156
	v_mul_f32_e32 v157, v105, v157
	v_mul_f32_e32 v172, v106, v154
	v_mul_f32_e32 v173, v107, v155
	v_mul_f32_e32 v154, v100, v164
	v_mul_f32_e32 v155, v101, v165
	v_mul_f32_e32 v174, v102, v158
	v_mul_f32_e32 v175, v103, v159
	v_mul_f32_e32 v158, v156, v156
	v_mul_f32_e32 v159, v157, v157
	v_or_b32_e32 v150, s6, v204
	v_fma_f32 v162, v162, v162, v158
	v_fma_f32 v163, v163, v163, v159
	v_mul_f32_e32 v158, v154, v154
	v_mul_f32_e32 v159, v155, v155
	s_mov_b32 s6, 0x300000
	v_fma_f32 v160, v160, v160, v158
	v_fma_f32 v161, v161, v161, v159
	v_cvt_pk_bf16_f32 v156, v156, v157
	v_cvt_pk_bf16_f32 v157, v172, v173
	v_cvt_pk_bf16_f32 v158, v154, v155
	v_add_co_u32_e32 v154, vcc, s6, v152
	v_cvt_pk_bf16_f32 v159, v174, v175
	v_mul_f32_e32 v176, v84, v84
	v_mul_f32_e32 v177, v85, v85
	s_nop 0
	v_addc_co_u32_e32 v155, vcc, 0, v153, vcc
	global_store_dwordx4 v[154:155], v[156:159], off
	v_mul_f32_e32 v164, v86, v86
	v_mul_f32_e32 v165, v87, v87
	v_fma_f32 v176, -v176, s64, v166
	v_fma_f32 v177, -v177, s64, v166
	v_mul_f32_e32 v156, v90, v90
	v_mul_f32_e32 v157, v91, v91
	v_mul_f32_e32 v158, v88, v88
	v_mul_f32_e32 v159, v89, v89
	v_fma_f32 v156, -v156, s64, v166
	v_fma_f32 v157, -v157, s64, v166
	v_fma_f32 v158, -v158, s64, v166
	v_fma_f32 v159, -v159, s64, v166
	v_mul_f32_e32 v156, v90, v156
	v_mul_f32_e32 v157, v91, v157
	v_mul_f32_e32 v158, v88, v158
	v_mul_f32_e32 v159, v89, v159
	v_mul_f32_e32 v176, v84, v176
	v_mul_f32_e32 v177, v85, v177
	v_fma_f32 v164, -v164, s64, v166
	v_fma_f32 v165, -v165, s64, v166
	v_exp_f32_e32 v158, v158
	v_exp_f32_e32 v159, v159
	v_exp_f32_e32 v156, v156
	v_exp_f32_e32 v157, v157
	v_exp_f32_e32 v176, v176
	v_exp_f32_e32 v177, v177
	v_mul_f32_e32 v164, v86, v164
	v_mul_f32_e32 v165, v87, v165
; __device__ __forceinline__ u32x4 pack8(f32x4 v0, f32x4 v1) { u32x4 w; w.x = cvt_pk_bf16(v0[0], v0[1]); w.y = cvt_pk_bf16(v0[2], v0[3]); w.z = cvt_pk_bf16(v1[0], v1[1]); w.w = cvt_pk_bf16(v1[2], v1[3]); return w; }
; __device__ __forceinline__ f32x4 gelu4(f32x4 v) { const f32x2 a = gelu2((f32x2){v[0], v[1]}), b = gelu2((f32x2){v[2], v[3]}); return (f32x4){a.x, a.y, b.x, b.y}; }
; __device__ __forceinline__ f32x2 gelu2(f32x2 x) { const f32x2 u = x * x, p = u * (0.044715f * -2.302208198f) + (-2.302208198f), t = x * p; f32x2 e; e.x = __builtin_amdgcn_exp2f(t.x); e.y = __builtin_amdgcn_exp2f(t.y);
;     const f32x2 d = e + 1.0f; f32x2 r; r.x = __builtin_amdgcn_rcpf(d.x); r.y = __builtin_amdgcn_rcpf(d.y); return x * r; }
;     __device__ __forceinline__ void operator()(const f32x4 (&acc)[2][2][4][2], const Unit& u, int ui, int wr, int wc, int fr, int fq) const {
;     ...
;                     for (int m = 0; m < 4; ++m) { const f32x4 g0 = gelu4(acc[ai][bj][m][0]), g1 = gelu4(acc[ai][bj][m][1]);
;                         sq0 += g0 * g0; sq1 += g1 * g1;
;                         *(u32x4*)(base + (size_t)(ai * 128 + m * 16) * MTOK + bj * 128) = pack8(g0, g1); }
	v_add_f32_e32 v158, 1.0, v158
	v_add_f32_e32 v159, 1.0, v159
	v_exp_f32_e32 v164, v164
	v_exp_f32_e32 v165, v165
	v_add_f32_e32 v156, 1.0, v156
	v_add_f32_e32 v157, 1.0, v157
	v_add_f32_e32 v176, 1.0, v176
	v_add_f32_e32 v177, 1.0, v177
	v_rcp_f32_e32 v158, v158
	v_rcp_f32_e32 v159, v159
	v_rcp_f32_e32 v156, v156
	v_rcp_f32_e32 v157, v157
	v_rcp_f32_e32 v178, v176
	v_rcp_f32_e32 v179, v177
	v_add_f32_e32 v164, 1.0, v164
	v_add_f32_e32 v165, 1.0, v165
	v_mul_f32_e32 v158, v88, v158
	v_mul_f32_e32 v159, v89, v159
	v_rcp_f32_e32 v164, v164
	v_rcp_f32_e32 v165, v165
	v_mul_f32_e32 v176, v90, v156
	v_mul_f32_e32 v177, v91, v157
	v_mul_f32_e32 v156, v84, v178
	v_mul_f32_e32 v157, v85, v179
	v_fma_f32 v162, v158, v158, v162
	v_fma_f32 v163, v159, v159, v163
	v_mul_f32_e32 v178, v86, v164
	v_mul_f32_e32 v179, v87, v165
	v_fma_f32 v164, v156, v156, v160
	v_fma_f32 v165, v157, v157, v161
	v_cvt_pk_bf16_f32 v158, v158, v159
	v_cvt_pk_bf16_f32 v159, v176, v177
	v_cvt_pk_bf16_f32 v160, v156, v157
	v_add_co_u32_e32 v156, vcc, s93, v152
	v_cvt_pk_bf16_f32 v161, v178, v179
	v_mul_f32_e32 v182, v68, v68
	v_mul_f32_e32 v183, v69, v69
	s_nop 0
	v_addc_co_u32_e32 v157, vcc, 0, v153, vcc
	global_store_dwordx4 v[156:157], v[158:161], off
	v_fma_f32 v182, -v182, s64, v166
	v_fma_f32 v183, -v183, s64, v166
	v_mul_f32_e32 v180, v70, v70
	v_mul_f32_e32 v181, v71, v71
	v_mul_f32_e32 v158, v74, v74
	v_mul_f32_e32 v159, v75, v75
	v_mul_f32_e32 v160, v72, v72
	v_mul_f32_e32 v161, v73, v73
	v_fma_f32 v158, -v158, s64, v166
	v_fma_f32 v159, -v159, s64, v166
	v_fma_f32 v160, -v160, s64, v166
	v_fma_f32 v161, -v161, s64, v166
	v_mul_f32_e32 v158, v74, v158
	v_mul_f32_e32 v159, v75, v159
	v_mul_f32_e32 v160, v72, v160
	v_mul_f32_e32 v161, v73, v161
	v_mul_f32_e32 v182, v68, v182
	v_mul_f32_e32 v183, v69, v183
	v_exp_f32_e32 v160, v160
	v_exp_f32_e32 v161, v161
	v_exp_f32_e32 v158, v158
	v_exp_f32_e32 v159, v159
	v_exp_f32_e32 v182, v182
	v_exp_f32_e32 v183, v183
	v_fma_f32 v180, -v180, s64, v166
	v_fma_f32 v181, -v181, s64, v166
	v_add_f32_e32 v160, 1.0, v160
	v_add_f32_e32 v161, 1.0, v161
	v_mul_f32_e32 v180, v70, v180
	v_mul_f32_e32 v181, v71, v181
	v_add_f32_e32 v158, 1.0, v158
	v_add_f32_e32 v159, 1.0, v159
	v_exp_f32_e32 v180, v180
	v_exp_f32_e32 v181, v181
	v_add_f32_e32 v182, 1.0, v182
	v_add_f32_e32 v183, 1.0, v183
	v_rcp_f32_e32 v160, v160
	v_rcp_f32_e32 v161, v161
	v_rcp_f32_e32 v158, v158
	v_rcp_f32_e32 v159, v159
	v_rcp_f32_e32 v182, v182
	v_rcp_f32_e32 v183, v183
	v_add_f32_e32 v180, 1.0, v180
	v_add_f32_e32 v181, 1.0, v181
	v_mul_f32_e32 v160, v72, v160
	v_mul_f32_e32 v161, v73, v161
	v_rcp_f32_e32 v184, v180
	v_rcp_f32_e32 v185, v181
	v_mul_f32_e32 v180, v74, v158
	v_mul_f32_e32 v181, v75, v159
	v_mul_f32_e32 v158, v68, v182
	v_mul_f32_e32 v159, v69, v183
	v_fma_f32 v188, v160, v160, v162
	v_fma_f32 v189, v161, v161, v163
	v_fma_f32 v164, v158, v158, v164
	v_fma_f32 v165, v159, v159, v165
	v_cvt_pk_bf16_f32 v160, v160, v161
	v_cvt_pk_bf16_f32 v161, v180, v181
	v_cvt_pk_bf16_f32 v162, v158, v159
	v_add_co_u32_e32 v158, vcc, s94, v152
	v_mul_f32_e32 v182, v70, v184
	v_mul_f32_e32 v183, v71, v185
	s_nop 0
	v_addc_co_u32_e32 v159, vcc, 0, v153, vcc
	v_cvt_pk_bf16_f32 v163, v182, v183
	global_store_dwordx4 v[158:159], v[160:163], off
	v_mul_f32_e32 v186, v52, v52
	v_mul_f32_e32 v187, v53, v53
	v_mul_f32_e32 v184, v54, v54
	v_mul_f32_e32 v185, v55, v55
	v_mul_f32_e32 v160, v58, v58
	v_mul_f32_e32 v161, v59, v59
	v_mul_f32_e32 v162, v56, v56
	v_mul_f32_e32 v163, v57, v57
	v_fma_f32 v160, -v160, s64, v166
	v_fma_f32 v161, -v161, s64, v166
	v_fma_f32 v162, -v162, s64, v166
	v_fma_f32 v163, -v163, s64, v166
	v_fma_f32 v186, -v186, s64, v166
	v_fma_f32 v187, -v187, s64, v166
	v_mul_f32_e32 v162, v56, v162
	v_mul_f32_e32 v163, v57, v163
	v_mul_f32_e32 v160, v58, v160
	v_mul_f32_e32 v161, v59, v161
	v_mul_f32_e32 v186, v52, v186
	v_mul_f32_e32 v187, v53, v187
	v_exp_f32_e32 v162, v162
	v_exp_f32_e32 v163, v163
	v_exp_f32_e32 v160, v160
	v_exp_f32_e32 v161, v161
	v_exp_f32_e32 v186, v186
	v_exp_f32_e32 v187, v187
	v_fma_f32 v184, -v184, s64, v166
	v_fma_f32 v185, -v185, s64, v166
	v_add_f32_e32 v162, 1.0, v162
	v_add_f32_e32 v163, 1.0, v163
	v_mul_f32_e32 v184, v54, v184
	v_mul_f32_e32 v185, v55, v185
	v_add_f32_e32 v160, 1.0, v160
	v_add_f32_e32 v161, 1.0, v161
	v_exp_f32_e32 v184, v184
	v_exp_f32_e32 v185, v185
	v_add_f32_e32 v186, 1.0, v186
	v_add_f32_e32 v187, 1.0, v187
	v_rcp_f32_e32 v162, v162
	v_rcp_f32_e32 v163, v163
	v_rcp_f32_e32 v160, v160
	v_rcp_f32_e32 v161, v161
	v_rcp_f32_e32 v186, v186
	v_rcp_f32_e32 v187, v187
	v_add_f32_e32 v184, 1.0, v184
	v_add_f32_e32 v185, 1.0, v185
	v_mul_f32_e32 v162, v56, v162
	v_mul_f32_e32 v163, v57, v163
	v_rcp_f32_e32 v190, v184
	v_rcp_f32_e32 v191, v185
	v_mul_f32_e32 v184, v58, v160
	v_mul_f32_e32 v185, v59, v161
	v_mul_f32_e32 v160, v52, v186
	v_mul_f32_e32 v161, v53, v187
	v_fma_f32 v192, v162, v162, v188
	v_fma_f32 v193, v163, v163, v189
	v_fma_f32 v194, v160, v160, v164
	v_fma_f32 v195, v161, v161, v165
	v_cvt_pk_bf16_f32 v162, v162, v163
	v_cvt_pk_bf16_f32 v163, v184, v185
	v_cvt_pk_bf16_f32 v164, v160, v161
	v_add_co_u32_e32 v160, vcc, s95, v152
	v_mul_f32_e32 v186, v54, v190
	v_mul_f32_e32 v187, v55, v191
	s_nop 0
	v_addc_co_u32_e32 v161, vcc, 0, v153, vcc
	v_cvt_pk_bf16_f32 v165, v186, v187
	global_store_dwordx4 v[160:161], v[162:165], off
	v_mul_f32_e32 v190, v36, v36
	v_mul_f32_e32 v191, v37, v37
	v_mul_f32_e32 v188, v38, v38
	v_mul_f32_e32 v189, v39, v39
	v_mul_f32_e32 v162, v42, v42
	v_mul_f32_e32 v163, v43, v43
	v_mul_f32_e32 v164, v40, v40
	v_mul_f32_e32 v165, v41, v41
	v_fma_f32 v162, -v162, s64, v166
; __device__ __forceinline__ float row16_sum(float x) { x += dpp<0xB1>(x); x += dpp<0x4E>(x); x += dpp<0x141>(x); x += dpp<0x128>(x); return x; }
; __device__ __forceinline__ u32x4 pack8(f32x4 v0, f32x4 v1) { u32x4 w; w.x = cvt_pk_bf16(v0[0], v0[1]); w.y = cvt_pk_bf16(v0[2], v0[3]); w.z = cvt_pk_bf16(v1[0], v1[1]); w.w = cvt_pk_bf16(v1[2], v1[3]); return w; }
; __device__ __forceinline__ f32x4 gelu4(f32x4 v) { const f32x2 a = gelu2((f32x2){v[0], v[1]}), b = gelu2((f32x2){v[2], v[3]}); return (f32x4){a.x, a.y, b.x, b.y}; }
; __device__ __forceinline__ f32x2 gelu2(f32x2 x) { const f32x2 u = x * x, p = u * (0.044715f * -2.302208198f) + (-2.302208198f), t = x * p; f32x2 e; e.x = __builtin_amdgcn_exp2f(t.x); e.y = __builtin_amdgcn_exp2f(t.y);
;     const f32x2 d = e + 1.0f; f32x2 r; r.x = __builtin_amdgcn_rcpf(d.x); r.y = __builtin_amdgcn_rcpf(d.y); return x * r; }
;     __device__ __forceinline__ void operator()(const f32x4 (&acc)[2][2][4][2], const Unit& u, int ui, int wr, int wc, int fr, int fq) const {
;     ...
;                     for (int m = 0; m < 4; ++m) { const f32x4 g0 = gelu4(acc[ai][bj][m][0]), g1 = gelu4(acc[ai][bj][m][1]);
;                         sq0 += g0 * g0; sq1 += g1 * g1;
;                         *(u32x4*)(base + (size_t)(ai * 128 + m * 16) * MTOK + bj * 128) = pack8(g0, g1); }
; #pragma unroll
;                 for (int j = 0; j < 4; ++j) { const float t0 = row16_sum(sq0[j]), t1 = row16_sum(sq1[j]); if (fr == 0) { pp[(size_t)(bj * 128 + j) * 8] = t0; pp[(size_t)(bj * 128 + 4 + j) * 8] = t1; } } }
	v_fma_f32 v163, -v163, s64, v166
	v_fma_f32 v164, -v164, s64, v166
	v_fma_f32 v165, -v165, s64, v166
	v_fma_f32 v190, -v190, s64, v166
	v_fma_f32 v191, -v191, s64, v166
	v_mul_f32_e32 v164, v40, v164
	v_mul_f32_e32 v165, v41, v165
	v_mul_f32_e32 v162, v42, v162
	v_mul_f32_e32 v163, v43, v163
	v_mul_f32_e32 v190, v36, v190
	v_mul_f32_e32 v191, v37, v191
	v_fma_f32 v188, -v188, s64, v166
	v_fma_f32 v189, -v189, s64, v166
	v_exp_f32_e32 v164, v164
	v_exp_f32_e32 v165, v165
	v_exp_f32_e32 v162, v162
	v_exp_f32_e32 v163, v163
	v_exp_f32_e32 v190, v190
	v_exp_f32_e32 v191, v191
	v_mul_f32_e32 v188, v38, v188
	v_mul_f32_e32 v189, v39, v189
	v_add_f32_e32 v164, 1.0, v164
	v_add_f32_e32 v165, 1.0, v165
	v_exp_f32_e32 v188, v188
	v_exp_f32_e32 v189, v189
	v_add_f32_e32 v162, 1.0, v162
	v_add_f32_e32 v163, 1.0, v163
	v_add_f32_e32 v190, 1.0, v190
	v_add_f32_e32 v191, 1.0, v191
	v_rcp_f32_e32 v164, v164
	v_rcp_f32_e32 v165, v165
	v_rcp_f32_e32 v162, v162
	v_rcp_f32_e32 v163, v163
	v_rcp_f32_e32 v190, v190
	v_rcp_f32_e32 v191, v191
	v_add_f32_e32 v188, 1.0, v188
	v_add_f32_e32 v189, 1.0, v189
	v_mul_f32_e32 v164, v40, v164
	v_mul_f32_e32 v165, v41, v165
	v_rcp_f32_e32 v196, v188
	v_rcp_f32_e32 v197, v189
	v_mul_f32_e32 v188, v42, v162
	v_mul_f32_e32 v189, v43, v163
	v_mul_f32_e32 v162, v36, v190
	v_mul_f32_e32 v163, v37, v191
	v_mul_f32_e32 v200, v20, v20
	v_mul_f32_e32 v201, v21, v21
	v_mul_f32_e32 v190, v38, v196
	v_mul_f32_e32 v191, v39, v197
	v_fma_f32 v196, v164, v164, v192
	v_fma_f32 v197, v165, v165, v193
	v_fma_f32 v198, v162, v162, v194
	v_fma_f32 v199, v163, v163, v195
	v_cvt_pk_bf16_f32 v192, v164, v165
	v_cvt_pk_bf16_f32 v193, v188, v189
	v_cvt_pk_bf16_f32 v194, v162, v163
	v_add_co_u32_e32 v162, vcc, s96, v152
	v_cvt_pk_bf16_f32 v195, v190, v191
	v_mul_f32_e32 v164, v26, v26
	v_mul_f32_e32 v165, v27, v27
	s_nop 0
	v_addc_co_u32_e32 v163, vcc, 0, v153, vcc
	global_store_dwordx4 v[162:163], v[192:195], off
	v_fma_f32 v164, -v164, s64, v166
	v_fma_f32 v165, -v165, s64, v166
	v_fma_f32 v200, -v200, s64, v166
	v_fma_f32 v201, -v201, s64, v166
	v_mul_f32_e32 v192, v24, v24
	v_mul_f32_e32 v193, v25, v25
	v_mul_f32_e32 v164, v26, v164
	v_mul_f32_e32 v165, v27, v165
	v_fma_f32 v192, -v192, s64, v166
	v_fma_f32 v193, -v193, s64, v166
	v_mul_f32_e32 v194, v22, v22
	v_mul_f32_e32 v195, v23, v23
	v_mul_f32_e32 v192, v24, v192
	v_mul_f32_e32 v193, v25, v193
	v_mul_f32_e32 v200, v20, v200
	v_mul_f32_e32 v201, v21, v201
	v_exp_f32_e32 v192, v192
	v_exp_f32_e32 v193, v193
	v_exp_f32_e32 v164, v164
	v_exp_f32_e32 v165, v165
	v_exp_f32_e32 v200, v200
	v_exp_f32_e32 v201, v201
	v_fma_f32 v194, -v194, s64, v166
	v_fma_f32 v195, -v195, s64, v166
	v_add_f32_e32 v192, 1.0, v192
	v_add_f32_e32 v193, 1.0, v193
	v_mul_f32_e32 v194, v22, v194
	v_mul_f32_e32 v195, v23, v195
	v_add_f32_e32 v164, 1.0, v164
	v_add_f32_e32 v165, 1.0, v165
	v_exp_f32_e32 v194, v194
	v_exp_f32_e32 v195, v195
	v_add_f32_e32 v200, 1.0, v200
	v_add_f32_e32 v201, 1.0, v201
	v_rcp_f32_e32 v192, v192
	v_rcp_f32_e32 v193, v193
	v_rcp_f32_e32 v164, v164
	v_rcp_f32_e32 v165, v165
	v_rcp_f32_e32 v200, v200
	v_rcp_f32_e32 v201, v201
	v_add_f32_e32 v194, 1.0, v194
	v_add_f32_e32 v195, 1.0, v195
	v_mul_f32_e32 v202, v24, v192
	v_mul_f32_e32 v203, v25, v193
	v_rcp_f32_e32 v194, v194
	v_rcp_f32_e32 v195, v195
	v_mul_f32_e32 v192, v26, v164
	v_mul_f32_e32 v193, v27, v165
	v_mul_f32_e32 v164, v20, v200
	v_mul_f32_e32 v165, v21, v201
	v_fma_f32 v210, v202, v202, v196
	v_fma_f32 v211, v203, v203, v197
	v_fma_f32 v212, v164, v164, v198
	v_fma_f32 v213, v165, v165, v199
	v_cvt_pk_bf16_f32 v196, v202, v203
	v_cvt_pk_bf16_f32 v197, v192, v193
	v_cvt_pk_bf16_f32 v198, v164, v165
	v_add_co_u32_e32 v164, vcc, s97, v152
	v_mul_f32_e32 v194, v22, v194
	v_mul_f32_e32 v195, v23, v195
	s_nop 0
	v_addc_co_u32_e32 v165, vcc, 0, v153, vcc
	v_cvt_pk_bf16_f32 v199, v194, v195
	global_store_dwordx4 v[164:165], v[196:199], off
	v_mul_f32_e32 v202, v4, v4
	v_mul_f32_e32 v203, v5, v5
	v_mul_f32_e32 v200, v6, v6
	v_mul_f32_e32 v201, v7, v7
	v_mul_f32_e32 v198, v8, v8
	v_mul_f32_e32 v199, v9, v9
	v_fma_f32 v202, -v202, s64, v166
	v_fma_f32 v203, -v203, s64, v166
	v_fma_f32 v198, -v198, s64, v166
	v_fma_f32 v199, -v199, s64, v166
	v_mul_f32_e32 v202, v4, v202
	v_mul_f32_e32 v203, v5, v203
	v_mul_f32_e32 v198, v8, v198
	v_mul_f32_e32 v199, v9, v199
	v_exp_f32_e32 v202, v202
	v_exp_f32_e32 v198, v198
	v_exp_f32_e32 v199, v199
	v_exp_f32_e32 v203, v203
	v_mul_f32_e32 v196, v10, v10
	v_mul_f32_e32 v197, v11, v11
	v_ashrrev_i32_e32 v151, 31, v150
	v_fma_f32 v196, -v196, s64, v166
	v_fma_f32 v197, -v197, s64, v166
	v_fma_f32 v167, -v201, s64, v166
	v_fma_f32 v166, -v200, s64, v166
	v_mul_f32_e32 v196, v10, v196
	v_mul_f32_e32 v197, v11, v197
	v_mul_f32_e32 v166, v6, v166
	v_mul_f32_e32 v167, v7, v167
	v_add_f32_e32 v198, 1.0, v198
	v_add_f32_e32 v199, 1.0, v199
	v_exp_f32_e32 v166, v166
	v_exp_f32_e32 v167, v167
	v_add_f32_e32 v200, 1.0, v202
	v_add_f32_e32 v201, 1.0, v203
	v_exp_f32_e32 v196, v196
	v_exp_f32_e32 v197, v197
	v_rcp_f32_e32 v198, v198
	v_rcp_f32_e32 v199, v199
	v_rcp_f32_e32 v200, v200
	v_rcp_f32_e32 v201, v201
	v_add_f32_e32 v166, 1.0, v166
	v_add_f32_e32 v167, 1.0, v167
	v_add_f32_e32 v196, 1.0, v196
	v_add_f32_e32 v197, 1.0, v197
	v_rcp_f32_e32 v166, v166
	v_rcp_f32_e32 v167, v167
	v_mul_f32_e32 v214, v8, v198
	v_mul_f32_e32 v215, v9, v199
	v_mul_f32_e32 v216, v4, v200
	v_mul_f32_e32 v217, v5, v201
	v_rcp_f32_e32 v196, v196
	v_rcp_f32_e32 v197, v197
	v_fma_f32 v202, v214, v214, v210
	v_fma_f32 v203, v215, v215, v211
	v_fma_f32 v198, v216, v216, v212
	v_fma_f32 v199, v217, v217, v213
	v_lshlrev_b64 v[150:151], 5, v[150:151]
	v_add_f32_dpp v140, v202, v202 quad_perm:[1,0,3,2] row_mask:0xf bank_mask:0xf bound_ctrl:1
	v_add_f32_dpp v198, v198, v198 quad_perm:[1,0,3,2] row_mask:0xf bank_mask:0xf bound_ctrl:1
	v_lshl_add_u64 v[150:151], s[54:55], 0, v[150:151]
	s_lshl_b32 s20, s25, 1
	v_add_f32_dpp v140, v140, v140 quad_perm:[2,3,0,1] row_mask:0xf bank_mask:0xf bound_ctrl:1
	v_add_f32_dpp v198, v198, v198 quad_perm:[2,3,0,1] row_mask:0xf bank_mask:0xf bound_ctrl:1
	v_lshl_add_u64 v[150:151], s[20:21], 2, v[150:151]
	s_mov_b32 s63, s21
	v_mul_f32_e32 v200, v6, v166
	v_mul_f32_e32 v201, v7, v167
	v_add_co_u32_e32 v166, vcc, s98, v152
	v_add_f32_dpp v140, v140, v140 row_half_mirror row_mask:0xf bank_mask:0xf bound_ctrl:1
	v_add_f32_dpp v198, v198, v198 row_half_mirror row_mask:0xf bank_mask:0xf bound_ctrl:1
	v_lshl_add_u64 v[150:151], v[150:151], 0, s[62:63]
	v_mul_f32_e32 v196, v10, v196
	v_mul_f32_e32 v197, v11, v197
	v_addc_co_u32_e32 v167, vcc, 0, v153, vcc
	v_mov_b32_dpp v202, v140 row_ror:8 row_mask:0xf bank_mask:0xf bound_ctrl:1
	v_mov_b32_dpp v209, v198 row_ror:8 row_mask:0xf bank_mask:0xf bound_ctrl:1
	v_cvt_pk_bf16_f32 v210, v214, v215
	v_cvt_pk_bf16_f32 v211, v196, v197
	v_cvt_pk_bf16_f32 v212, v216, v217
	v_cvt_pk_bf16_f32 v213, v200, v201
	global_store_dwordx4 v[166:167], v[210:213], off
	s_and_saveexec_b64 s[6:7], s[10:11]
	s_cbranch_execz .LBB0_173
; __device__ __forceinline__ float row16_sum(float x) { x += dpp<0xB1>(x); x += dpp<0x4E>(x); x += dpp<0x141>(x); x += dpp<0x128>(x); return x; }
; __device__ __forceinline__ u32x4 pack8(f32x4 v0, f32x4 v1) { u32x4 w; w.x = cvt_pk_bf16(v0[0], v0[1]); w.y = cvt_pk_bf16(v0[2], v0[3]); w.z = cvt_pk_bf16(v1[0], v1[1]); w.w = cvt_pk_bf16(v1[2], v1[3]); return w; }
;     __device__ __forceinline__ void operator()(const f32x4 (&acc)[2][2][4][2], const Unit& u, int ui, int wr, int wc, int fr, int fq) const {
;     ...
;                         sq0 += g0 * g0; sq1 += g1 * g1;
;                         *(u32x4*)(base + (size_t)(ai * 128 + m * 16) * MTOK + bj * 128) = pack8(g0, g1); }
; #pragma unroll
;                 for (int j = 0; j < 4; ++j) { const float t0 = row16_sum(sq0[j]), t1 = row16_sum(sq1[j]); if (fr == 0) { pp[(size_t)(bj * 128 + j) * 8] = t0; pp[(size_t)(bj * 128 + 4 + j) * 8] = t1; } } }
	v_add_f32_e32 v140, v140, v202
	v_add_f32_e32 v198, v198, v209
	global_store_dword v[150:151], v140, off
	global_store_dword v[150:151], v198, off offset:128
.LBB0_173:
	s_or_b64 exec, exec, s[6:7]
	v_mul_f32_e32 v172, v172, v172
	v_mul_f32_e32 v173, v173, v173
	v_add_f32_dpp v140, v203, v203 quad_perm:[1,0,3,2] row_mask:0xf bank_mask:0xf bound_ctrl:1
	v_fma_f32 v168, v168, v168, v172
	v_fma_f32 v169, v169, v169, v173
	v_mul_f32_e32 v172, v174, v174
	v_mul_f32_e32 v173, v175, v175
	v_fma_f32 v168, v176, v176, v168
	v_fma_f32 v169, v177, v177, v169
	v_fma_f32 v170, v170, v170, v172
	v_fma_f32 v171, v171, v171, v173
	v_fma_f32 v168, v180, v180, v168
	v_fma_f32 v169, v181, v181, v169
	v_fma_f32 v170, v178, v178, v170
	v_fma_f32 v171, v179, v179, v171
	v_fma_f32 v168, v184, v184, v168
	v_fma_f32 v169, v185, v185, v169
	v_fma_f32 v170, v182, v182, v170
	v_fma_f32 v171, v183, v183, v171
	v_fma_f32 v168, v188, v188, v168
	v_fma_f32 v169, v189, v189, v169
	v_fma_f32 v170, v186, v186, v170
	v_fma_f32 v171, v187, v187, v171
	v_fma_f32 v168, v192, v192, v168
	v_fma_f32 v169, v193, v193, v169
	v_fma_f32 v170, v190, v190, v170
	v_fma_f32 v171, v191, v191, v171
	v_add_f32_dpp v140, v140, v140 quad_perm:[2,3,0,1] row_mask:0xf bank_mask:0xf bound_ctrl:1
	v_fma_f32 v172, v194, v194, v170
	v_fma_f32 v173, v195, v195, v171
	v_fma_f32 v170, v196, v196, v168
	v_fma_f32 v171, v197, v197, v169
	v_fma_f32 v168, v200, v200, v172
	v_fma_f32 v169, v201, v201, v173
	v_add_f32_dpp v173, v199, v199 quad_perm:[1,0,3,2] row_mask:0xf bank_mask:0xf bound_ctrl:1
	v_add_f32_dpp v140, v140, v140 row_half_mirror row_mask:0xf bank_mask:0xf bound_ctrl:1
	s_nop 0
	v_add_f32_dpp v173, v173, v173 quad_perm:[2,3,0,1] row_mask:0xf bank_mask:0xf bound_ctrl:1
	v_mov_b32_dpp v172, v140 row_ror:8 row_mask:0xf bank_mask:0xf bound_ctrl:1
	s_nop 0
	v_add_f32_dpp v173, v173, v173 row_half_mirror row_mask:0xf bank_mask:0xf bound_ctrl:1
	s_nop 1
	v_mov_b32_dpp v174, v173 row_ror:8 row_mask:0xf bank_mask:0xf bound_ctrl:1
	s_and_saveexec_b64 s[6:7], s[10:11]
	s_cbranch_execz .LBB0_175
	v_add_f32_e32 v140, v140, v172
	v_add_f32_e32 v173, v173, v174
	global_store_dword v[150:151], v140, off offset:32
	global_store_dword v[150:151], v173, off offset:160

; __device__ __forceinline__ float row16_sum(float x) { x += dpp<0xB1>(x); x += dpp<0x4E>(x); x += dpp<0x141>(x); x += dpp<0x128>(x); return x; }
; __device__ __forceinline__ u32x4 pack8(f32x4 v0, f32x4 v1) { u32x4 w; w.x = cvt_pk_bf16(v0[0], v0[1]); w.y = cvt_pk_bf16(v0[2], v0[3]); w.z = cvt_pk_bf16(v1[0], v1[1]); w.w = cvt_pk_bf16(v1[2], v1[3]); return w; }
; __device__ __forceinline__ f32x4 gelu4(f32x4 v) { const f32x2 a = gelu2((f32x2){v[0], v[1]}), b = gelu2((f32x2){v[2], v[3]}); return (f32x4){a.x, a.y, b.x, b.y}; }
; __device__ __forceinline__ f32x2 gelu2(f32x2 x) { const f32x2 u = x * x, p = u * (0.044715f * -2.302208198f) + (-2.302208198f), t = x * p; f32x2 e; e.x = __builtin_amdgcn_exp2f(t.x); e.y = __builtin_amdgcn_exp2f(t.y);
;     const f32x2 d = e + 1.0f; f32x2 r; r.x = __builtin_amdgcn_rcpf(d.x); r.y = __builtin_amdgcn_rcpf(d.y); return x * r; }
;     __device__ __forceinline__ void operator()(const f32x4 (&acc)[2][2][4][2], const Unit& u, int ui, int wr, int wc, int fr, int fq) const {
;     ...
;                     for (int m = 0; m < 4; ++m) { const f32x4 g0 = gelu4(acc[ai][bj][m][0]), g1 = gelu4(acc[ai][bj][m][1]);
;                         sq0 += g0 * g0; sq1 += g1 * g1;
;                         *(u32x4*)(base + (size_t)(ai * 128 + m * 16) * MTOK + bj * 128) = pack8(g0, g1); }
; #pragma unroll
;                 for (int j = 0; j < 4; ++j) { const float t0 = row16_sum(sq0[j]), t1 = row16_sum(sq1[j]); if (fr == 0) { pp[(size_t)(bj * 128 + j) * 8] = t0; pp[(size_t)(bj * 128 + 4 + j) * 8] = t1; } } }
.LBB0_179:
	s_or_b64 exec, exec, s[6:7]
	v_mul_f32_e32 v168, v126, v126
	v_mul_f32_e32 v169, v127, v127
	v_mul_f32_e32 v170, v124, v124
	v_mul_f32_e32 v171, v125, v125
	v_mov_b64_e32 v[172:173], s[66:67]
	v_mul_f32_e32 v174, v114, v114
	v_mul_f32_e32 v175, v115, v115
	v_fma_f32 v170, -v170, s64, v172
	v_fma_f32 v171, -v171, s64, v172
	v_fma_f32 v168, -v168, s64, v172
	v_fma_f32 v169, -v169, s64, v172
	v_mul_f32_e32 v176, v112, v112
	v_mul_f32_e32 v177, v113, v113
	v_fma_f32 v174, -v174, s64, v172
	v_fma_f32 v175, -v175, s64, v172
	v_mul_f32_e32 v170, v124, v170
	v_mul_f32_e32 v171, v125, v171
	v_mul_f32_e32 v168, v126, v168
	v_mul_f32_e32 v169, v127, v169
	v_fma_f32 v176, -v176, s64, v172
	v_fma_f32 v177, -v177, s64, v172
	v_mul_f32_e32 v174, v114, v174
	v_mul_f32_e32 v175, v115, v175
	v_exp_f32_e32 v170, v170
	v_exp_f32_e32 v171, v171
	v_exp_f32_e32 v168, v168
	v_exp_f32_e32 v169, v169
	v_mul_f32_e32 v176, v112, v176
	v_mul_f32_e32 v177, v113, v177
	v_exp_f32_e32 v174, v174
	v_exp_f32_e32 v175, v175
	v_exp_f32_e32 v176, v176
	v_exp_f32_e32 v177, v177
	v_add_f32_e32 v170, 1.0, v170
	v_add_f32_e32 v171, 1.0, v171
	v_add_f32_e32 v168, 1.0, v168
	v_add_f32_e32 v169, 1.0, v169
	v_add_f32_e32 v174, 1.0, v174
	v_add_f32_e32 v175, 1.0, v175
	v_rcp_f32_e32 v170, v170
	v_rcp_f32_e32 v171, v171
	v_rcp_f32_e32 v168, v168
	v_rcp_f32_e32 v169, v169
	v_add_f32_e32 v176, 1.0, v176
	v_add_f32_e32 v177, 1.0, v177
	v_rcp_f32_e32 v174, v174
	v_rcp_f32_e32 v175, v175
	v_rcp_f32_e32 v176, v176
	v_rcp_f32_e32 v177, v177
	v_mul_f32_e32 v178, v124, v170
	v_mul_f32_e32 v179, v125, v171
	v_mul_f32_e32 v168, v126, v168
	v_mul_f32_e32 v169, v127, v169
	v_mul_f32_e32 v170, v114, v174
	v_mul_f32_e32 v171, v115, v175
	v_cvt_pk_bf16_f32 v174, v178, v179
	v_cvt_pk_bf16_f32 v175, v168, v169
	v_mul_f32_e32 v180, v112, v176
	v_mul_f32_e32 v181, v113, v177
	v_mul_f32_e32 v182, v96, v96
	v_mul_f32_e32 v183, v97, v97
	v_cvt_pk_bf16_f32 v176, v180, v181
	v_cvt_pk_bf16_f32 v177, v170, v171
	global_store_dwordx4 v[152:153], v[174:177], off offset:256
	v_fma_f32 v182, -v182, s64, v172
	v_fma_f32 v183, -v183, s64, v172
	v_mul_f32_e32 v152, v110, v110
	v_mul_f32_e32 v153, v111, v111
	v_mul_f32_e32 v174, v108, v108
	v_mul_f32_e32 v175, v109, v109
	v_mul_f32_e32 v176, v98, v98
	v_mul_f32_e32 v177, v99, v99
	v_fma_f32 v174, -v174, s64, v172
	v_fma_f32 v175, -v175, s64, v172
	v_fma_f32 v176, -v176, s64, v172
	v_fma_f32 v177, -v177, s64, v172
	v_mul_f32_e32 v174, v108, v174
	v_mul_f32_e32 v175, v109, v175
	v_mul_f32_e32 v182, v96, v182
	v_mul_f32_e32 v183, v97, v183
	v_exp_f32_e32 v174, v174
	v_exp_f32_e32 v175, v175
	v_mul_f32_e32 v176, v98, v176
	v_mul_f32_e32 v177, v99, v177
	v_fma_f32 v152, -v152, s64, v172
	v_fma_f32 v153, -v153, s64, v172
	v_exp_f32_e32 v182, v182
	v_exp_f32_e32 v183, v183
	v_exp_f32_e32 v176, v176
	v_exp_f32_e32 v177, v177
	v_mul_f32_e32 v152, v110, v152
	v_mul_f32_e32 v153, v111, v153
	v_add_f32_e32 v174, 1.0, v174
	v_add_f32_e32 v175, 1.0, v175
	v_exp_f32_e32 v152, v152
	v_exp_f32_e32 v153, v153
	v_rcp_f32_e32 v174, v174
	v_rcp_f32_e32 v175, v175
	v_add_f32_e32 v182, 1.0, v182
	v_add_f32_e32 v183, 1.0, v183
	v_add_f32_e32 v176, 1.0, v176
	v_add_f32_e32 v177, 1.0, v177
	v_rcp_f32_e32 v182, v182
	v_rcp_f32_e32 v183, v183
	v_rcp_f32_e32 v176, v176
	v_rcp_f32_e32 v177, v177
	v_add_f32_e32 v152, 1.0, v152
	v_add_f32_e32 v153, 1.0, v153
	v_mul_f32_e32 v184, v108, v174
	v_mul_f32_e32 v185, v109, v175
	v_rcp_f32_e32 v152, v152
	v_rcp_f32_e32 v153, v153
	v_mul_f32_e32 v182, v96, v182
	v_mul_f32_e32 v183, v97, v183
	v_mul_f32_e32 v174, v98, v176
	v_mul_f32_e32 v175, v99, v177
	v_mul_f32_e32 v176, v184, v184
	v_mul_f32_e32 v177, v185, v185
	v_mul_f32_e32 v152, v110, v152
	v_mul_f32_e32 v153, v111, v153
	v_fma_f32 v186, v178, v178, v176
	v_fma_f32 v187, v179, v179, v177
	v_mul_f32_e32 v176, v182, v182
	v_mul_f32_e32 v177, v183, v183
	s_nop 0
	v_fma_f32 v180, v180, v180, v176
	v_fma_f32 v181, v181, v181, v177
	v_cvt_pk_bf16_f32 v176, v184, v185
	v_cvt_pk_bf16_f32 v177, v152, v153
	v_cvt_pk_bf16_f32 v178, v182, v183
	v_cvt_pk_bf16_f32 v179, v174, v175
	v_mul_f32_e32 v182, v80, v80
	v_mul_f32_e32 v183, v81, v81
	global_store_dwordx4 v[154:155], v[176:179], off offset:256
	v_mul_f32_e32 v154, v94, v94
	v_mul_f32_e32 v155, v95, v95
	v_fma_f32 v182, -v182, s64, v172
	v_fma_f32 v183, -v183, s64, v172
	v_mul_f32_e32 v176, v92, v92
	v_mul_f32_e32 v177, v93, v93
	v_mul_f32_e32 v178, v82, v82
	v_mul_f32_e32 v179, v83, v83
	v_fma_f32 v176, -v176, s64, v172
	v_fma_f32 v177, -v177, s64, v172
	v_fma_f32 v154, -v154, s64, v172
	v_fma_f32 v155, -v155, s64, v172
	v_mul_f32_e32 v182, v80, v182
	v_mul_f32_e32 v183, v81, v183
	v_fma_f32 v178, -v178, s64, v172
	v_fma_f32 v179, -v179, s64, v172
	v_mul_f32_e32 v176, v92, v176
	v_mul_f32_e32 v177, v93, v177
	v_mul_f32_e32 v154, v94, v154
	v_mul_f32_e32 v155, v95, v155
	v_exp_f32_e32 v182, v182
	v_exp_f32_e32 v183, v183
	v_mul_f32_e32 v178, v82, v178
	v_mul_f32_e32 v179, v83, v179
	v_exp_f32_e32 v176, v176
	v_exp_f32_e32 v177, v177
	v_exp_f32_e32 v154, v154
	v_exp_f32_e32 v155, v155
	v_exp_f32_e32 v178, v178
	v_exp_f32_e32 v179, v179
	v_add_f32_e32 v182, 1.0, v182
	v_add_f32_e32 v183, 1.0, v183
	v_add_f32_e32 v176, 1.0, v176
	v_add_f32_e32 v177, 1.0, v177
	v_add_f32_e32 v154, 1.0, v154
	v_add_f32_e32 v155, 1.0, v155
	v_rcp_f32_e32 v182, v182
	v_rcp_f32_e32 v183, v183
	v_add_f32_e32 v178, 1.0, v178
	v_add_f32_e32 v179, 1.0, v179
	v_rcp_f32_e32 v176, v176
	v_rcp_f32_e32 v177, v177
	v_rcp_f32_e32 v154, v154
	v_rcp_f32_e32 v155, v155
	v_rcp_f32_e32 v178, v178
	v_rcp_f32_e32 v179, v179
	v_mul_f32_e32 v182, v80, v182
	v_mul_f32_e32 v183, v81, v183
; __device__ __forceinline__ float row16_sum(float x) { x += dpp<0xB1>(x); x += dpp<0x4E>(x); x += dpp<0x141>(x); x += dpp<0x128>(x); return x; }
; __device__ __forceinline__ u32x4 pack8(f32x4 v0, f32x4 v1) { u32x4 w; w.x = cvt_pk_bf16(v0[0], v0[1]); w.y = cvt_pk_bf16(v0[2], v0[3]); w.z = cvt_pk_bf16(v1[0], v1[1]); w.w = cvt_pk_bf16(v1[2], v1[3]); return w; }
; __device__ __forceinline__ f32x4 gelu4(f32x4 v) { const f32x2 a = gelu2((f32x2){v[0], v[1]}), b = gelu2((f32x2){v[2], v[3]}); return (f32x4){a.x, a.y, b.x, b.y}; }
; __device__ __forceinline__ f32x2 gelu2(f32x2 x) { const f32x2 u = x * x, p = u * (0.044715f * -2.302208198f) + (-2.302208198f), t = x * p; f32x2 e; e.x = __builtin_amdgcn_exp2f(t.x); e.y = __builtin_amdgcn_exp2f(t.y);
;     const f32x2 d = e + 1.0f; f32x2 r; r.x = __builtin_amdgcn_rcpf(d.x); r.y = __builtin_amdgcn_rcpf(d.y); return x * r; }
;     __device__ __forceinline__ void operator()(const f32x4 (&acc)[2][2][4][2], const Unit& u, int ui, int wr, int wc, int fr, int fq) const {
;     ...
;                     for (int m = 0; m < 4; ++m) { const f32x4 g0 = gelu4(acc[ai][bj][m][0]), g1 = gelu4(acc[ai][bj][m][1]);
;                         sq0 += g0 * g0; sq1 += g1 * g1;
;                         *(u32x4*)(base + (size_t)(ai * 128 + m * 16) * MTOK + bj * 128) = pack8(g0, g1); }
; #pragma unroll
;                 for (int j = 0; j < 4; ++j) { const float t0 = row16_sum(sq0[j]), t1 = row16_sum(sq1[j]); if (fr == 0) { pp[(size_t)(bj * 128 + j) * 8] = t0; pp[(size_t)(bj * 128 + 4 + j) * 8] = t1; } } }
	v_mul_f32_e32 v184, v92, v176
	v_mul_f32_e32 v185, v93, v177
	v_mul_f32_e32 v154, v94, v154
	v_mul_f32_e32 v155, v95, v155
	v_mul_f32_e32 v176, v82, v178
	v_mul_f32_e32 v177, v83, v179
	v_fma_f32 v188, v182, v182, v180
	v_fma_f32 v189, v183, v183, v181
	v_cvt_pk_bf16_f32 v178, v184, v185
	v_cvt_pk_bf16_f32 v179, v154, v155
	v_cvt_pk_bf16_f32 v180, v182, v183
	v_cvt_pk_bf16_f32 v181, v176, v177
	v_mul_f32_e32 v182, v64, v64
	v_mul_f32_e32 v183, v65, v65
	global_store_dwordx4 v[156:157], v[178:181], off offset:256
	v_mul_f32_e32 v156, v78, v78
	v_mul_f32_e32 v157, v79, v79
	v_fma_f32 v182, -v182, s64, v172
	v_fma_f32 v183, -v183, s64, v172
	v_mul_f32_e32 v178, v76, v76
	v_mul_f32_e32 v179, v77, v77
	v_mul_f32_e32 v180, v66, v66
	v_mul_f32_e32 v181, v67, v67
	v_fma_f32 v178, -v178, s64, v172
	v_fma_f32 v179, -v179, s64, v172
	v_fma_f32 v156, -v156, s64, v172
	v_fma_f32 v157, -v157, s64, v172
	v_mul_f32_e32 v182, v64, v182
	v_mul_f32_e32 v183, v65, v183
	v_fma_f32 v180, -v180, s64, v172
	v_fma_f32 v181, -v181, s64, v172
	v_mul_f32_e32 v178, v76, v178
	v_mul_f32_e32 v179, v77, v179
	v_mul_f32_e32 v156, v78, v156
	v_mul_f32_e32 v157, v79, v157
	v_exp_f32_e32 v182, v182
	v_exp_f32_e32 v183, v183
	v_mul_f32_e32 v180, v66, v180
	v_mul_f32_e32 v181, v67, v181
	v_exp_f32_e32 v178, v178
	v_exp_f32_e32 v179, v179
	v_exp_f32_e32 v156, v156
	v_exp_f32_e32 v157, v157
	v_exp_f32_e32 v180, v180
	v_exp_f32_e32 v181, v181
	v_add_f32_e32 v182, 1.0, v182
	v_add_f32_e32 v183, 1.0, v183
	v_add_f32_e32 v178, 1.0, v178
	v_add_f32_e32 v179, 1.0, v179
	v_add_f32_e32 v156, 1.0, v156
	v_add_f32_e32 v157, 1.0, v157
	v_rcp_f32_e32 v182, v182
	v_rcp_f32_e32 v183, v183
	v_add_f32_e32 v180, 1.0, v180
	v_add_f32_e32 v181, 1.0, v181
	v_rcp_f32_e32 v178, v178
	v_rcp_f32_e32 v179, v179
	v_rcp_f32_e32 v156, v156
	v_rcp_f32_e32 v157, v157
	v_rcp_f32_e32 v180, v180
	v_rcp_f32_e32 v181, v181
	v_mul_f32_e32 v182, v64, v182
	v_mul_f32_e32 v183, v65, v183
	v_fma_f32 v186, v184, v184, v186
	v_fma_f32 v187, v185, v185, v187
	v_mul_f32_e32 v184, v76, v178
	v_mul_f32_e32 v185, v77, v179
	v_mul_f32_e32 v156, v78, v156
	v_mul_f32_e32 v157, v79, v157
	v_mul_f32_e32 v178, v66, v180
	v_mul_f32_e32 v179, v67, v181
	v_fma_f32 v188, v182, v182, v188
	v_fma_f32 v189, v183, v183, v189
	v_cvt_pk_bf16_f32 v180, v184, v185
	v_cvt_pk_bf16_f32 v181, v156, v157
	v_cvt_pk_bf16_f32 v182, v182, v183
	v_cvt_pk_bf16_f32 v183, v178, v179
	v_fma_f32 v186, v184, v184, v186
	v_fma_f32 v187, v185, v185, v187
	global_store_dwordx4 v[158:159], v[180:183], off offset:256
	v_mul_f32_e32 v158, v62, v62
	v_mul_f32_e32 v159, v63, v63
	v_mul_f32_e32 v184, v48, v48
	v_mul_f32_e32 v185, v49, v49
	v_mul_f32_e32 v180, v60, v60
	v_mul_f32_e32 v181, v61, v61
	v_mul_f32_e32 v182, v50, v50
	v_mul_f32_e32 v183, v51, v51
	v_fma_f32 v180, -v180, s64, v172
	v_fma_f32 v181, -v181, s64, v172
	v_fma_f32 v158, -v158, s64, v172
	v_fma_f32 v159, -v159, s64, v172
	v_fma_f32 v184, -v184, s64, v172
	v_fma_f32 v185, -v185, s64, v172
	v_fma_f32 v182, -v182, s64, v172
	v_fma_f32 v183, -v183, s64, v172
	v_mul_f32_e32 v180, v60, v180
	v_mul_f32_e32 v181, v61, v181
	v_mul_f32_e32 v158, v62, v158
	v_mul_f32_e32 v159, v63, v159
	v_mul_f32_e32 v184, v48, v184
	v_mul_f32_e32 v185, v49, v185
	v_mul_f32_e32 v182, v50, v182
	v_mul_f32_e32 v183, v51, v183
	v_exp_f32_e32 v180, v180
	v_exp_f32_e32 v181, v181
	v_exp_f32_e32 v158, v158
	v_exp_f32_e32 v159, v159
	v_exp_f32_e32 v184, v184
	v_exp_f32_e32 v185, v185
	v_exp_f32_e32 v182, v182
	v_exp_f32_e32 v183, v183
	v_add_f32_e32 v180, 1.0, v180
	v_add_f32_e32 v181, 1.0, v181
	v_add_f32_e32 v158, 1.0, v158
	v_add_f32_e32 v159, 1.0, v159
	v_add_f32_e32 v184, 1.0, v184
	v_add_f32_e32 v185, 1.0, v185
	v_add_f32_e32 v182, 1.0, v182
	v_add_f32_e32 v183, 1.0, v183
	v_rcp_f32_e32 v180, v180
	v_rcp_f32_e32 v181, v181
	v_rcp_f32_e32 v158, v158
	v_rcp_f32_e32 v159, v159
	v_rcp_f32_e32 v184, v184
	v_rcp_f32_e32 v185, v185
	v_rcp_f32_e32 v182, v182
	v_rcp_f32_e32 v183, v183
	v_mul_f32_e32 v190, v60, v180
	v_mul_f32_e32 v191, v61, v181
	v_mul_f32_e32 v158, v62, v158
	v_mul_f32_e32 v159, v63, v159
	v_mul_f32_e32 v184, v48, v184
	v_mul_f32_e32 v185, v49, v185
	v_mul_f32_e32 v180, v50, v182
	v_mul_f32_e32 v181, v51, v183
	v_cvt_pk_bf16_f32 v182, v190, v191
	v_cvt_pk_bf16_f32 v183, v158, v159
	v_fma_f32 v188, v184, v184, v188
	v_fma_f32 v189, v185, v185, v189
	v_cvt_pk_bf16_f32 v184, v184, v185
	v_cvt_pk_bf16_f32 v185, v180, v181
	global_store_dwordx4 v[160:161], v[182:185], off offset:256
	v_fma_f32 v186, v190, v190, v186
	v_fma_f32 v187, v191, v191, v187
	v_mul_f32_e32 v160, v46, v46
	v_mul_f32_e32 v161, v47, v47
	v_mul_f32_e32 v182, v44, v44
	v_mul_f32_e32 v183, v45, v45
	v_mul_f32_e32 v184, v34, v34
	v_mul_f32_e32 v185, v35, v35
	v_fma_f32 v182, -v182, s64, v172
	v_fma_f32 v183, -v183, s64, v172
	v_mul_f32_e32 v190, v32, v32
	v_mul_f32_e32 v191, v33, v33
	v_mul_f32_e32 v182, v44, v182
	v_mul_f32_e32 v183, v45, v183
	v_fma_f32 v160, -v160, s64, v172
	v_fma_f32 v161, -v161, s64, v172
	v_fma_f32 v190, -v190, s64, v172
	v_fma_f32 v191, -v191, s64, v172
	v_fma_f32 v184, -v184, s64, v172
	v_fma_f32 v185, -v185, s64, v172
	v_exp_f32_e32 v182, v182
	v_exp_f32_e32 v183, v183
	v_mul_f32_e32 v160, v46, v160
	v_mul_f32_e32 v161, v47, v161
	v_mul_f32_e32 v190, v32, v190
	v_mul_f32_e32 v191, v33, v191
	v_mul_f32_e32 v184, v34, v184
	v_mul_f32_e32 v185, v35, v185
	v_exp_f32_e32 v160, v160
	v_exp_f32_e32 v161, v161
	v_exp_f32_e32 v190, v190
	v_exp_f32_e32 v191, v191
	v_exp_f32_e32 v184, v184
	v_exp_f32_e32 v185, v185
	v_add_f32_e32 v182, 1.0, v182
	v_add_f32_e32 v183, 1.0, v183
	v_add_f32_e32 v160, 1.0, v160
	v_add_f32_e32 v161, 1.0, v161
; __device__ __forceinline__ float row16_sum(float x) { x += dpp<0xB1>(x); x += dpp<0x4E>(x); x += dpp<0x141>(x); x += dpp<0x128>(x); return x; }
; __device__ __forceinline__ u32x4 pack8(f32x4 v0, f32x4 v1) { u32x4 w; w.x = cvt_pk_bf16(v0[0], v0[1]); w.y = cvt_pk_bf16(v0[2], v0[3]); w.z = cvt_pk_bf16(v1[0], v1[1]); w.w = cvt_pk_bf16(v1[2], v1[3]); return w; }
; __device__ __forceinline__ f32x4 gelu4(f32x4 v) { const f32x2 a = gelu2((f32x2){v[0], v[1]}), b = gelu2((f32x2){v[2], v[3]}); return (f32x4){a.x, a.y, b.x, b.y}; }
; __device__ __forceinline__ f32x2 gelu2(f32x2 x) { const f32x2 u = x * x, p = u * (0.044715f * -2.302208198f) + (-2.302208198f), t = x * p; f32x2 e; e.x = __builtin_amdgcn_exp2f(t.x); e.y = __builtin_amdgcn_exp2f(t.y);
;     const f32x2 d = e + 1.0f; f32x2 r; r.x = __builtin_amdgcn_rcpf(d.x); r.y = __builtin_amdgcn_rcpf(d.y); return x * r; }
;     __device__ __forceinline__ void operator()(const f32x4 (&acc)[2][2][4][2], const Unit& u, int ui, int wr, int wc, int fr, int fq) const {
;     ...
;                     for (int m = 0; m < 4; ++m) { const f32x4 g0 = gelu4(acc[ai][bj][m][0]), g1 = gelu4(acc[ai][bj][m][1]);
;                         sq0 += g0 * g0; sq1 += g1 * g1;
;                         *(u32x4*)(base + (size_t)(ai * 128 + m * 16) * MTOK + bj * 128) = pack8(g0, g1); }
; #pragma unroll
;                 for (int j = 0; j < 4; ++j) { const float t0 = row16_sum(sq0[j]), t1 = row16_sum(sq1[j]); if (fr == 0) { pp[(size_t)(bj * 128 + j) * 8] = t0; pp[(size_t)(bj * 128 + 4 + j) * 8] = t1; } } }
	v_rcp_f32_e32 v182, v182
	v_rcp_f32_e32 v183, v183
	v_add_f32_e32 v190, 1.0, v190
	v_add_f32_e32 v191, 1.0, v191
	v_add_f32_e32 v184, 1.0, v184
	v_add_f32_e32 v185, 1.0, v185
	v_rcp_f32_e32 v160, v160
	v_rcp_f32_e32 v161, v161
	v_rcp_f32_e32 v190, v190
	v_rcp_f32_e32 v191, v191
	v_rcp_f32_e32 v184, v184
	v_rcp_f32_e32 v185, v185
	v_mul_f32_e32 v192, v44, v182
	v_mul_f32_e32 v193, v45, v183
	v_mul_f32_e32 v160, v46, v160
	v_mul_f32_e32 v161, v47, v161
	v_mul_f32_e32 v190, v32, v190
	v_mul_f32_e32 v191, v33, v191
	v_mul_f32_e32 v182, v34, v184
	v_mul_f32_e32 v183, v35, v185
	v_fma_f32 v194, v192, v192, v186
	v_fma_f32 v195, v193, v193, v187
	v_cvt_pk_bf16_f32 v184, v192, v193
	v_cvt_pk_bf16_f32 v185, v160, v161
	v_cvt_pk_bf16_f32 v186, v190, v191
	v_cvt_pk_bf16_f32 v187, v182, v183
	v_fma_f32 v188, v190, v190, v188
	v_fma_f32 v189, v191, v191, v189
	global_store_dwordx4 v[162:163], v[184:187], off offset:256
	v_mul_f32_e32 v162, v30, v30
	v_mul_f32_e32 v163, v31, v31
	v_mul_f32_e32 v190, v16, v16
	v_mul_f32_e32 v191, v17, v17
	v_mul_f32_e32 v184, v28, v28
	v_mul_f32_e32 v185, v29, v29
	v_mul_f32_e32 v186, v18, v18
	v_mul_f32_e32 v187, v19, v19
	v_fma_f32 v184, -v184, s64, v172
	v_fma_f32 v185, -v185, s64, v172
	v_fma_f32 v162, -v162, s64, v172
	v_fma_f32 v163, -v163, s64, v172
	v_fma_f32 v190, -v190, s64, v172
	v_fma_f32 v191, -v191, s64, v172
	v_fma_f32 v186, -v186, s64, v172
	v_fma_f32 v187, -v187, s64, v172
	v_mul_f32_e32 v184, v28, v184
	v_mul_f32_e32 v185, v29, v185
	v_mul_f32_e32 v162, v30, v162
	v_mul_f32_e32 v163, v31, v163
	v_mul_f32_e32 v190, v16, v190
	v_mul_f32_e32 v191, v17, v191
	v_mul_f32_e32 v186, v18, v186
	v_mul_f32_e32 v187, v19, v187
	v_exp_f32_e32 v184, v184
	v_exp_f32_e32 v185, v185
	v_exp_f32_e32 v162, v162
	v_exp_f32_e32 v163, v163
	v_exp_f32_e32 v190, v190
	v_exp_f32_e32 v191, v191
	v_exp_f32_e32 v186, v186
	v_exp_f32_e32 v187, v187
	v_add_f32_e32 v184, 1.0, v184
	v_add_f32_e32 v185, 1.0, v185
	v_add_f32_e32 v162, 1.0, v162
	v_add_f32_e32 v163, 1.0, v163
	v_add_f32_e32 v190, 1.0, v190
	v_add_f32_e32 v191, 1.0, v191
	v_add_f32_e32 v186, 1.0, v186
	v_add_f32_e32 v187, 1.0, v187
	v_rcp_f32_e32 v184, v184
	v_rcp_f32_e32 v185, v185
	v_rcp_f32_e32 v162, v162
	v_rcp_f32_e32 v163, v163
	v_rcp_f32_e32 v190, v190
	v_rcp_f32_e32 v191, v191
	v_rcp_f32_e32 v186, v186
	v_rcp_f32_e32 v187, v187
	v_mul_f32_e32 v192, v28, v184
	v_mul_f32_e32 v193, v29, v185
	v_mul_f32_e32 v162, v30, v162
	v_mul_f32_e32 v163, v31, v163
	v_mul_f32_e32 v190, v16, v190
	v_mul_f32_e32 v191, v17, v191
	v_mul_f32_e32 v184, v18, v186
	v_mul_f32_e32 v185, v19, v187
	v_cvt_pk_bf16_f32 v186, v192, v193
	v_cvt_pk_bf16_f32 v187, v162, v163
	v_fma_f32 v196, v190, v190, v188
	v_fma_f32 v197, v191, v191, v189
	v_cvt_pk_bf16_f32 v188, v190, v191
	v_cvt_pk_bf16_f32 v189, v184, v185
	global_store_dwordx4 v[164:165], v[186:189], off offset:256
	v_mul_f32_e32 v190, v0, v0
	v_mul_f32_e32 v191, v1, v1
	v_mul_f32_e32 v164, v14, v14
	v_mul_f32_e32 v165, v15, v15
	v_mul_f32_e32 v186, v12, v12
	v_mul_f32_e32 v187, v13, v13
	v_mul_f32_e32 v188, v2, v2
	v_mul_f32_e32 v189, v3, v3
	v_fma_f32 v186, -v186, s64, v172
	v_fma_f32 v187, -v187, s64, v172
	v_fma_f32 v190, -v190, s64, v172
	v_fma_f32 v191, -v191, s64, v172
	v_mul_f32_e32 v186, v12, v186
	v_mul_f32_e32 v187, v13, v187
	v_fma_f32 v164, -v164, s64, v172
	v_fma_f32 v165, -v165, s64, v172
	v_mul_f32_e32 v190, v0, v190
	v_mul_f32_e32 v191, v1, v191
	v_fma_f32 v173, -v189, s64, v172
	v_fma_f32 v172, -v188, s64, v172
	v_exp_f32_e32 v186, v186
	v_exp_f32_e32 v187, v187
	v_exp_f32_e32 v190, v190
	v_exp_f32_e32 v191, v191
	v_mul_f32_e32 v172, v2, v172
	v_mul_f32_e32 v173, v3, v173
	v_mul_f32_e32 v164, v14, v164
	v_mul_f32_e32 v165, v15, v165
	v_exp_f32_e32 v172, v172
	v_exp_f32_e32 v173, v173
	v_exp_f32_e32 v164, v164
	v_exp_f32_e32 v165, v165
	v_add_f32_e32 v186, 1.0, v186
	v_add_f32_e32 v187, 1.0, v187
	v_add_f32_e32 v188, 1.0, v190
	v_add_f32_e32 v189, 1.0, v191
	v_rcp_f32_e32 v186, v186
	v_rcp_f32_e32 v187, v187
	v_rcp_f32_e32 v188, v188
	v_rcp_f32_e32 v189, v189
	v_add_f32_e32 v172, 1.0, v172
	v_add_f32_e32 v173, 1.0, v173
	v_add_f32_e32 v164, 1.0, v164
	v_add_f32_e32 v165, 1.0, v165
	v_rcp_f32_e32 v172, v172
	v_rcp_f32_e32 v173, v173
	v_rcp_f32_e32 v164, v164
	v_rcp_f32_e32 v165, v165
	v_fma_f32 v194, v192, v192, v194
	v_fma_f32 v195, v193, v193, v195
	v_mul_f32_e32 v190, v12, v186
	v_mul_f32_e32 v191, v13, v187
	v_mul_f32_e32 v192, v0, v188
	v_mul_f32_e32 v193, v1, v189
	v_mul_f32_e32 v186, v2, v172
	v_mul_f32_e32 v187, v3, v173
	v_fma_f32 v188, v190, v190, v194
	v_fma_f32 v189, v191, v191, v195
	v_fma_f32 v172, v192, v192, v196
	v_fma_f32 v173, v193, v193, v197
	v_mul_f32_e32 v164, v14, v164
	v_mul_f32_e32 v165, v15, v165
	v_cvt_pk_bf16_f32 v190, v190, v191
	v_add_f32_dpp v140, v188, v188 quad_perm:[1,0,3,2] row_mask:0xf bank_mask:0xf bound_ctrl:1
	v_cvt_pk_bf16_f32 v191, v164, v165
	v_cvt_pk_bf16_f32 v192, v192, v193
	v_cvt_pk_bf16_f32 v193, v186, v187
	global_store_dwordx4 v[166:167], v[190:193], off offset:256
	v_add_f32_dpp v167, v172, v172 quad_perm:[1,0,3,2] row_mask:0xf bank_mask:0xf bound_ctrl:1
	v_add_f32_dpp v140, v140, v140 quad_perm:[2,3,0,1] row_mask:0xf bank_mask:0xf bound_ctrl:1
	s_nop 0
	v_add_f32_dpp v167, v167, v167 quad_perm:[2,3,0,1] row_mask:0xf bank_mask:0xf bound_ctrl:1
	v_add_f32_dpp v140, v140, v140 row_half_mirror row_mask:0xf bank_mask:0xf bound_ctrl:1
	s_nop 0
	v_add_f32_dpp v167, v167, v167 row_half_mirror row_mask:0xf bank_mask:0xf bound_ctrl:1
	v_mov_b32_dpp v166, v140 row_ror:8 row_mask:0xf bank_mask:0xf bound_ctrl:1
	s_nop 0
	v_mov_b32_dpp v172, v167 row_ror:8 row_mask:0xf bank_mask:0xf bound_ctrl:1
	s_and_saveexec_b64 s[6:7], s[10:11]
	s_cbranch_execz .LBB0_181
	v_add_f32_e32 v140, v140, v166
	v_add_co_u32_e32 v166, vcc, 0x1000, v150
	v_add_f32_e32 v172, v167, v172
	s_nop 0
	v_addc_co_u32_e32 v167, vcc, 0, v151, vcc
	global_store_dword v[166:167], v140, off
	global_store_dword v[166:167], v172, off offset:128
; __device__ __forceinline__ float row16_sum(float x) { x += dpp<0xB1>(x); x += dpp<0x4E>(x); x += dpp<0x141>(x); x += dpp<0x128>(x); return x; }
; __device__ __forceinline__ u32x4 pack8(f32x4 v0, f32x4 v1) { u32x4 w; w.x = cvt_pk_bf16(v0[0], v0[1]); w.y = cvt_pk_bf16(v0[2], v0[3]); w.z = cvt_pk_bf16(v1[0], v1[1]); w.w = cvt_pk_bf16(v1[2], v1[3]); return w; }
;     __device__ __forceinline__ void operator()(const f32x4 (&acc)[2][2][4][2], const Unit& u, int ui, int wr, int wc, int fr, int fq) const {
;     ...
;                         sq0 += g0 * g0; sq1 += g1 * g1;
;                         *(u32x4*)(base + (size_t)(ai * 128 + m * 16) * MTOK + bj * 128) = pack8(g0, g1); }
; #pragma unroll
;                 for (int j = 0; j < 4; ++j) { const float t0 = row16_sum(sq0[j]), t1 = row16_sum(sq1[j]); if (fr == 0) { pp[(size_t)(bj * 128 + j) * 8] = t0; pp[(size_t)(bj * 128 + 4 + j) * 8] = t1; } } }
.LBB0_181:
	s_or_b64 exec, exec, s[6:7]
	v_mul_f32_e32 v152, v152, v152
	v_mul_f32_e32 v153, v153, v153
	v_mul_f32_e32 v166, v174, v174
	v_mul_f32_e32 v167, v175, v175
	v_fma_f32 v152, v168, v168, v152
	v_fma_f32 v153, v169, v169, v153
	v_fma_f32 v166, v170, v170, v166
	v_fma_f32 v167, v171, v171, v167
	v_fma_f32 v152, v154, v154, v152
	v_fma_f32 v153, v155, v155, v153
	v_fma_f32 v154, v176, v176, v166
	v_fma_f32 v155, v177, v177, v167
	v_fma_f32 v152, v156, v156, v152
	v_fma_f32 v153, v157, v157, v153
	v_fma_f32 v154, v178, v178, v154
	v_fma_f32 v155, v179, v179, v155
	v_fma_f32 v152, v158, v158, v152
	v_fma_f32 v153, v159, v159, v153
	v_fma_f32 v154, v180, v180, v154
	v_fma_f32 v155, v181, v181, v155
	v_fma_f32 v152, v160, v160, v152
	v_fma_f32 v153, v161, v161, v153
	v_fma_f32 v154, v182, v182, v154
	v_fma_f32 v155, v183, v183, v155
	v_fma_f32 v152, v162, v162, v152
	v_fma_f32 v153, v163, v163, v153
	v_fma_f32 v156, v184, v184, v154
	v_fma_f32 v157, v185, v185, v155
	v_fma_f32 v154, v164, v164, v152
	v_fma_f32 v155, v165, v165, v153
	v_fma_f32 v152, v186, v186, v156
	v_fma_f32 v153, v187, v187, v157
	v_add_f32_dpp v140, v189, v189 quad_perm:[1,0,3,2] row_mask:0xf bank_mask:0xf bound_ctrl:1
	v_add_f32_dpp v157, v173, v173 quad_perm:[1,0,3,2] row_mask:0xf bank_mask:0xf bound_ctrl:1
	s_nop 0
	v_add_f32_dpp v140, v140, v140 quad_perm:[2,3,0,1] row_mask:0xf bank_mask:0xf bound_ctrl:1
	v_add_f32_dpp v157, v157, v157 quad_perm:[2,3,0,1] row_mask:0xf bank_mask:0xf bound_ctrl:1
	s_nop 0
	v_add_f32_dpp v140, v140, v140 row_half_mirror row_mask:0xf bank_mask:0xf bound_ctrl:1
	v_add_f32_dpp v157, v157, v157 row_half_mirror row_mask:0xf bank_mask:0xf bound_ctrl:1
	s_nop 0
	v_mov_b32_dpp v156, v140 row_ror:8 row_mask:0xf bank_mask:0xf bound_ctrl:1
	v_mov_b32_dpp v158, v157 row_ror:8 row_mask:0xf bank_mask:0xf bound_ctrl:1
	s_and_saveexec_b64 s[6:7], s[10:11]
	s_cbranch_execz .LBB0_183
	v_add_f32_e32 v140, v140, v156
	v_add_co_u32_e32 v156, vcc, 0x1000, v150
	v_add_f32_e32 v158, v157, v158
	s_nop 0
	v_addc_co_u32_e32 v157, vcc, 0, v151, vcc
	global_store_dword v[156:157], v140, off offset:32
	global_store_dword v[156:157], v158, off offset:160

; __device__ __forceinline__ u32x4 pack8(f32x4 v0, f32x4 v1) { u32x4 w; w.x = cvt_pk_bf16(v0[0], v0[1]); w.y = cvt_pk_bf16(v0[2], v0[3]); w.z = cvt_pk_bf16(v1[0], v1[1]); w.w = cvt_pk_bf16(v1[2], v1[3]); return w; }
; __device__ __forceinline__ f32x4 g1_4(f32x4 v, f32x4 g) { const f32x2 a = g1_2((f32x2){v[0], v[1]}, (f32x2){g[0], g[1]}), b = g1_2((f32x2){v[2], v[3]}, (f32x2){g[2], g[3]}); return (f32x4){a.x, a.y, b.x, b.y}; }
; __device__ __forceinline__ f32x2 g1_2(f32x2 x, f32x2 g) { const f32x2 u = x * x, p = u * (0.044715f * -2.302208198f) + (-2.302208198f), t = x * p, tg = g * (-LOG2E);
;     f32x2 e1, e2; e1.x = __builtin_amdgcn_exp2f(t.x); e1.y = __builtin_amdgcn_exp2f(t.y); e2.x = __builtin_amdgcn_exp2f(tg.x); e2.y = __builtin_amdgcn_exp2f(tg.y);
;     const f32x2 d = (e1 + 1.0f) * (e2 + 1.0f); f32x2 r; r.x = __builtin_amdgcn_rcpf(d.x); r.y = __builtin_amdgcn_rcpf(d.y); return x * r; }
;     __device__ __forceinline__ void operator()(const f32x4 (&acc)[2][2][4][2], const Unit& u, int ui, int wr, int wc, int fr, int fq) const {
;     ...
;             bf16_t* base = (bf16_t*)(ws + WS_U) + (size_t)(u.pm * 256 + wr * 64 + fr) * DM + pn * 128 + wc * 32 + 8 * fq;
; #pragma unroll
;             for (int ai = 0; ai < 2; ++ai)
; #pragma unroll
;                 for (int m = 0; m < 4; ++m) {
;                     const f32x4 g0 = g1_4(acc[ai][0][m][0], acc[ai][1][m][0]), g1 = g1_4(acc[ai][0][m][1], acc[ai][1][m][1]);
;                     *(u32x4*)(base + (size_t)(ai * 128 + m * 16) * DM) = pack8(g0, g1); }
.LBB0_189:
	v_lshl_add_u32 v150, s76, 8, v129
	v_ashrrev_i32_e32 v151, 31, v150
	v_lshlrev_b64 v[150:151], 11, v[150:151]
	s_lshl_b32 s6, s74, 7
	v_lshl_add_u64 v[150:151], s[56:57], 0, v[150:151]
	s_ashr_i32 s7, s6, 31
	v_lshl_add_u64 v[150:151], s[6:7], 1, v[150:151]
	s_lshl_b32 s20, s88, 1
	v_lshl_add_u64 v[152:153], v[150:151], 0, s[20:21]
	v_lshlrev_b32_e32 v140, 1, v130
	v_mul_f32_e32 v124, s60, v124
	v_mul_f32_e32 v125, s60, v125
	v_mov_b64_e32 v[150:151], s[66:67]
	v_exp_f32_e32 v156, v124
	v_exp_f32_e32 v157, v125
	v_lshl_add_u64 v[124:125], v[152:153], 0, v[140:141]
	v_mul_f32_e32 v152, v122, v122
	v_mul_f32_e32 v153, v123, v123
	v_mul_f32_e32 v126, s60, v126
	v_mul_f32_e32 v127, s60, v127
	v_fma_f32 v152, -v152, s64, v150
	v_fma_f32 v153, -v153, s64, v150
	v_exp_f32_e32 v126, v126
	v_mul_f32_e32 v152, v122, v152
	v_mul_f32_e32 v153, v123, v153
	v_exp_f32_e32 v127, v127
	v_exp_f32_e32 v152, v152
	v_exp_f32_e32 v153, v153
	v_mul_f32_e32 v154, v120, v120
	v_mul_f32_e32 v155, v121, v121
	v_add_f32_e32 v126, 1.0, v126
	v_add_f32_e32 v127, 1.0, v127
	v_fma_f32 v154, -v154, s64, v150
	v_fma_f32 v155, -v155, s64, v150
	v_add_f32_e32 v152, 1.0, v152
	v_add_f32_e32 v153, 1.0, v153
	v_mul_f32_e32 v154, v120, v154
	v_mul_f32_e32 v155, v121, v155
	v_mul_f32_e32 v126, v152, v126
	v_mul_f32_e32 v127, v153, v127
	v_mul_f32_e32 v152, v116, v116
	v_mul_f32_e32 v153, v117, v117
	v_exp_f32_e32 v154, v154
	v_fma_f32 v152, -v152, s64, v150
	v_fma_f32 v153, -v153, s64, v150
	v_exp_f32_e32 v155, v155
	v_mul_f32_e32 v152, v116, v152
	v_mul_f32_e32 v153, v117, v153
	v_mul_f32_e32 v112, s60, v112
	v_mul_f32_e32 v113, s60, v113
	v_exp_f32_e32 v152, v152
	v_exp_f32_e32 v153, v153
	v_exp_f32_e32 v112, v112
	v_exp_f32_e32 v113, v113
	v_add_f32_e32 v154, 1.0, v154
	v_add_f32_e32 v155, 1.0, v155
	v_add_f32_e32 v156, 1.0, v156
	v_add_f32_e32 v157, 1.0, v157
	v_add_f32_e32 v152, 1.0, v152
	v_add_f32_e32 v153, 1.0, v153
	v_mul_f32_e32 v154, v154, v156
	v_mul_f32_e32 v155, v155, v157
	v_mul_f32_e32 v156, v118, v118
	v_mul_f32_e32 v157, v119, v119
	v_add_f32_e32 v112, 1.0, v112
	v_add_f32_e32 v113, 1.0, v113
	v_mul_f32_e32 v114, s60, v114
	v_mul_f32_e32 v115, s60, v115
	v_mul_f32_e32 v112, v152, v112
	v_mul_f32_e32 v113, v153, v113
	v_fma_f32 v152, -v156, s64, v150
	v_fma_f32 v153, -v157, s64, v150
	v_exp_f32_e32 v114, v114
	v_mul_f32_e32 v152, v118, v152
	v_mul_f32_e32 v153, v119, v153
	v_exp_f32_e32 v115, v115
	v_exp_f32_e32 v152, v152
	v_exp_f32_e32 v153, v153
	v_rcp_f32_e32 v154, v154
	v_add_f32_e32 v114, 1.0, v114
	v_add_f32_e32 v115, 1.0, v115
	v_rcp_f32_e32 v155, v155
	v_add_f32_e32 v152, 1.0, v152
	v_add_f32_e32 v153, 1.0, v153
	v_rcp_f32_e32 v126, v126
	v_rcp_f32_e32 v127, v127
	v_rcp_f32_e32 v112, v112
	v_rcp_f32_e32 v113, v113
	v_mul_f32_e32 v114, v152, v114
	v_mul_f32_e32 v115, v153, v115
	v_mul_f32_e32 v120, v120, v154
	v_mul_f32_e32 v121, v121, v155
	v_rcp_f32_e32 v114, v114
	v_rcp_f32_e32 v115, v115
	v_mul_f32_e32 v122, v122, v126
	v_mul_f32_e32 v123, v123, v127
	v_mul_f32_e32 v116, v116, v112
	v_mul_f32_e32 v117, v117, v113
	v_cvt_pk_bf16_f32 v112, v120, v121
	v_cvt_pk_bf16_f32 v113, v122, v123
	v_mul_f32_e32 v118, v118, v114
	v_mul_f32_e32 v119, v119, v115
	v_cvt_pk_bf16_f32 v114, v116, v117
	v_mul_f32_e32 v110, s60, v110
	v_mul_f32_e32 v111, s60, v111
	v_cvt_pk_bf16_f32 v115, v118, v119
	global_store_dwordx4 v[124:125], v[112:115], off
	v_exp_f32_e32 v110, v110
	v_exp_f32_e32 v111, v111
	v_mul_f32_e32 v112, v106, v106
	v_mul_f32_e32 v113, v107, v107
	v_mul_f32_e32 v116, v104, v104
	v_mul_f32_e32 v117, v105, v105
	v_fma_f32 v112, -v112, s64, v150
	v_fma_f32 v113, -v113, s64, v150
	v_add_f32_e32 v110, 1.0, v110
	v_add_f32_e32 v111, 1.0, v111
	v_mul_f32_e32 v112, v106, v112
	v_mul_f32_e32 v113, v107, v113
	v_fma_f32 v116, -v116, s64, v150
	v_fma_f32 v117, -v117, s64, v150
	v_exp_f32_e32 v112, v112
	v_exp_f32_e32 v113, v113
	v_mul_f32_e32 v116, v104, v116
	v_mul_f32_e32 v117, v105, v117
	v_mul_f32_e32 v108, s60, v108
	v_mul_f32_e32 v109, s60, v109
	v_exp_f32_e32 v116, v116
	v_add_f32_e32 v112, 1.0, v112
	v_add_f32_e32 v113, 1.0, v113
	v_exp_f32_e32 v117, v117
	v_mul_f32_e32 v110, v112, v110
	v_mul_f32_e32 v111, v113, v111
	v_mul_f32_e32 v112, v100, v100
	v_mul_f32_e32 v113, v101, v101
	v_exp_f32_e32 v108, v108
	v_fma_f32 v112, -v112, s64, v150
	v_fma_f32 v113, -v113, s64, v150
	v_exp_f32_e32 v109, v109
	v_mul_f32_e32 v112, v100, v112
	v_mul_f32_e32 v113, v101, v113
	v_mul_f32_e32 v96, s60, v96
	v_mul_f32_e32 v97, s60, v97
	v_exp_f32_e32 v112, v112
	v_exp_f32_e32 v113, v113
	v_exp_f32_e32 v96, v96
	v_exp_f32_e32 v97, v97
	v_add_f32_e32 v114, 1.0, v116
	v_add_f32_e32 v115, 1.0, v117
	v_add_f32_e32 v108, 1.0, v108
	v_add_f32_e32 v109, 1.0, v109
	v_add_f32_e32 v112, 1.0, v112
	v_add_f32_e32 v113, 1.0, v113
	v_mul_f32_e32 v108, v114, v108
	v_mul_f32_e32 v109, v115, v109
	v_mul_f32_e32 v114, v102, v102
	v_mul_f32_e32 v115, v103, v103
	v_add_f32_e32 v96, 1.0, v96
	v_add_f32_e32 v97, 1.0, v97
	v_mul_f32_e32 v98, s60, v98
	v_mul_f32_e32 v99, s60, v99
	v_mul_f32_e32 v96, v112, v96
	v_mul_f32_e32 v97, v113, v97
	v_fma_f32 v112, -v114, s64, v150
	v_fma_f32 v113, -v115, s64, v150
	v_exp_f32_e32 v98, v98
	v_mul_f32_e32 v112, v102, v112
	v_mul_f32_e32 v113, v103, v113
	v_exp_f32_e32 v99, v99
	v_exp_f32_e32 v112, v112
	v_exp_f32_e32 v113, v113
	v_rcp_f32_e32 v96, v96
	v_add_f32_e32 v98, 1.0, v98
	v_add_f32_e32 v99, 1.0, v99
	v_rcp_f32_e32 v97, v97
	v_add_f32_e32 v112, 1.0, v112
	v_add_f32_e32 v113, 1.0, v113
	v_rcp_f32_e32 v108, v108
	v_mul_f32_e32 v98, v112, v98
	v_mul_f32_e32 v99, v113, v99
	v_rcp_f32_e32 v109, v109
	v_rcp_f32_e32 v110, v110
	v_rcp_f32_e32 v111, v111
; __device__ __forceinline__ u32x4 pack8(f32x4 v0, f32x4 v1) { u32x4 w; w.x = cvt_pk_bf16(v0[0], v0[1]); w.y = cvt_pk_bf16(v0[2], v0[3]); w.z = cvt_pk_bf16(v1[0], v1[1]); w.w = cvt_pk_bf16(v1[2], v1[3]); return w; }
; __device__ __forceinline__ f32x4 g1_4(f32x4 v, f32x4 g) { const f32x2 a = g1_2((f32x2){v[0], v[1]}, (f32x2){g[0], g[1]}), b = g1_2((f32x2){v[2], v[3]}, (f32x2){g[2], g[3]}); return (f32x4){a.x, a.y, b.x, b.y}; }
; __device__ __forceinline__ f32x2 g1_2(f32x2 x, f32x2 g) { const f32x2 u = x * x, p = u * (0.044715f * -2.302208198f) + (-2.302208198f), t = x * p, tg = g * (-LOG2E);
;     f32x2 e1, e2; e1.x = __builtin_amdgcn_exp2f(t.x); e1.y = __builtin_amdgcn_exp2f(t.y); e2.x = __builtin_amdgcn_exp2f(tg.x); e2.y = __builtin_amdgcn_exp2f(tg.y);
;     const f32x2 d = (e1 + 1.0f) * (e2 + 1.0f); f32x2 r; r.x = __builtin_amdgcn_rcpf(d.x); r.y = __builtin_amdgcn_rcpf(d.y); return x * r; }
;     __device__ __forceinline__ void operator()(const f32x4 (&acc)[2][2][4][2], const Unit& u, int ui, int wr, int wc, int fr, int fq) const {
;     ...
;             bf16_t* base = (bf16_t*)(ws + WS_U) + (size_t)(u.pm * 256 + wr * 64 + fr) * DM + pn * 128 + wc * 32 + 8 * fq;
; #pragma unroll
;             for (int ai = 0; ai < 2; ++ai)
; #pragma unroll
;                 for (int m = 0; m < 4; ++m) {
;                     const f32x4 g0 = g1_4(acc[ai][0][m][0], acc[ai][1][m][0]), g1 = g1_4(acc[ai][0][m][1], acc[ai][1][m][1]);
;                     *(u32x4*)(base + (size_t)(ai * 128 + m * 16) * DM) = pack8(g0, g1); }
	v_rcp_f32_e32 v98, v98
	v_rcp_f32_e32 v99, v99
	v_mul_f32_e32 v100, v100, v96
	v_mul_f32_e32 v101, v101, v97
	s_mov_b32 s6, 0x8000
	v_mul_f32_e32 v104, v104, v108
	v_mul_f32_e32 v105, v105, v109
	v_mul_f32_e32 v106, v106, v110
	v_mul_f32_e32 v107, v107, v111
	v_mul_f32_e32 v102, v102, v98
	v_mul_f32_e32 v103, v103, v99
	v_cvt_pk_bf16_f32 v96, v104, v105
	v_cvt_pk_bf16_f32 v97, v106, v107
	v_cvt_pk_bf16_f32 v98, v100, v101
	v_add_co_u32_e32 v100, vcc, s6, v124
	v_cvt_pk_bf16_f32 v99, v102, v103
	v_mul_f32_e32 v94, s60, v94
	v_mul_f32_e32 v95, s60, v95
	s_nop 0
	v_addc_co_u32_e32 v101, vcc, 0, v125, vcc
	global_store_dwordx4 v[100:101], v[96:99], off
	v_exp_f32_e32 v94, v94
	v_exp_f32_e32 v95, v95
	v_mul_f32_e32 v96, v90, v90
	v_mul_f32_e32 v97, v91, v91
	v_mul_f32_e32 v102, v88, v88
	v_mul_f32_e32 v103, v89, v89
	v_fma_f32 v96, -v96, s64, v150
	v_fma_f32 v97, -v97, s64, v150
	v_add_f32_e32 v94, 1.0, v94
	v_add_f32_e32 v95, 1.0, v95
	v_mul_f32_e32 v96, v90, v96
	v_mul_f32_e32 v97, v91, v97
	v_fma_f32 v102, -v102, s64, v150
	v_fma_f32 v103, -v103, s64, v150
	v_exp_f32_e32 v96, v96
	v_exp_f32_e32 v97, v97
	v_mul_f32_e32 v102, v88, v102
	v_mul_f32_e32 v103, v89, v103
	v_mul_f32_e32 v92, s60, v92
	v_mul_f32_e32 v93, s60, v93
	v_exp_f32_e32 v102, v102
	v_add_f32_e32 v96, 1.0, v96
	v_add_f32_e32 v97, 1.0, v97
	v_exp_f32_e32 v103, v103
	v_mul_f32_e32 v94, v96, v94
	v_mul_f32_e32 v95, v97, v95
	v_mul_f32_e32 v96, v84, v84
	v_mul_f32_e32 v97, v85, v85
	v_exp_f32_e32 v92, v92
	v_fma_f32 v96, -v96, s64, v150
	v_fma_f32 v97, -v97, s64, v150
	v_exp_f32_e32 v93, v93
	v_mul_f32_e32 v96, v84, v96
	v_mul_f32_e32 v97, v85, v97
	v_mul_f32_e32 v80, s60, v80
	v_mul_f32_e32 v81, s60, v81
	v_exp_f32_e32 v96, v96
	v_exp_f32_e32 v97, v97
	v_exp_f32_e32 v80, v80
	v_exp_f32_e32 v81, v81
	v_add_f32_e32 v98, 1.0, v102
	v_add_f32_e32 v99, 1.0, v103
	v_add_f32_e32 v92, 1.0, v92
	v_add_f32_e32 v93, 1.0, v93
	v_add_f32_e32 v96, 1.0, v96
	v_add_f32_e32 v97, 1.0, v97
	v_mul_f32_e32 v92, v98, v92
	v_mul_f32_e32 v93, v99, v93
	v_mul_f32_e32 v98, v86, v86
	v_mul_f32_e32 v99, v87, v87
	v_add_f32_e32 v80, 1.0, v80
	v_add_f32_e32 v81, 1.0, v81
	v_mul_f32_e32 v82, s60, v82
	v_mul_f32_e32 v83, s60, v83
	v_mul_f32_e32 v80, v96, v80
	v_mul_f32_e32 v81, v97, v81
	v_fma_f32 v96, -v98, s64, v150
	v_fma_f32 v97, -v99, s64, v150
	v_exp_f32_e32 v82, v82
	v_mul_f32_e32 v96, v86, v96
	v_mul_f32_e32 v97, v87, v97
	v_exp_f32_e32 v83, v83
	v_exp_f32_e32 v96, v96
	v_exp_f32_e32 v97, v97
	v_rcp_f32_e32 v80, v80
	v_add_f32_e32 v82, 1.0, v82
	v_add_f32_e32 v83, 1.0, v83
	v_rcp_f32_e32 v81, v81
	v_add_f32_e32 v96, 1.0, v96
	v_add_f32_e32 v97, 1.0, v97
	v_rcp_f32_e32 v92, v92
	v_mul_f32_e32 v82, v96, v82
	v_mul_f32_e32 v83, v97, v83
	v_rcp_f32_e32 v93, v93
	v_rcp_f32_e32 v94, v94
	v_rcp_f32_e32 v95, v95
	v_rcp_f32_e32 v82, v82
	v_rcp_f32_e32 v83, v83
	v_mul_f32_e32 v84, v84, v80
	v_mul_f32_e32 v85, v85, v81
	s_mov_b32 s6, 0x10000
	v_mul_f32_e32 v88, v88, v92
	v_mul_f32_e32 v89, v89, v93
	v_mul_f32_e32 v90, v90, v94
	v_mul_f32_e32 v91, v91, v95
	v_mul_f32_e32 v86, v86, v82
	v_mul_f32_e32 v87, v87, v83
	v_cvt_pk_bf16_f32 v80, v88, v89
	v_cvt_pk_bf16_f32 v81, v90, v91
	v_cvt_pk_bf16_f32 v82, v84, v85
	v_add_co_u32_e32 v84, vcc, s6, v124
	v_cvt_pk_bf16_f32 v83, v86, v87
	v_mul_f32_e32 v78, s60, v78
	v_mul_f32_e32 v79, s60, v79
	s_nop 0
	v_addc_co_u32_e32 v85, vcc, 0, v125, vcc
	global_store_dwordx4 v[84:85], v[80:83], off
	v_exp_f32_e32 v78, v78
	v_exp_f32_e32 v79, v79
	v_mul_f32_e32 v80, v74, v74
	v_mul_f32_e32 v81, v75, v75
	v_mul_f32_e32 v86, v72, v72
	v_mul_f32_e32 v87, v73, v73
	v_fma_f32 v80, -v80, s64, v150
	v_fma_f32 v81, -v81, s64, v150
	v_add_f32_e32 v78, 1.0, v78
	v_add_f32_e32 v79, 1.0, v79
	v_mul_f32_e32 v80, v74, v80
	v_mul_f32_e32 v81, v75, v81
	v_fma_f32 v86, -v86, s64, v150
	v_fma_f32 v87, -v87, s64, v150
	v_exp_f32_e32 v80, v80
	v_exp_f32_e32 v81, v81
	v_mul_f32_e32 v86, v72, v86
	v_mul_f32_e32 v87, v73, v87
	v_mul_f32_e32 v76, s60, v76
	v_mul_f32_e32 v77, s60, v77
	v_exp_f32_e32 v86, v86
	v_add_f32_e32 v80, 1.0, v80
	v_add_f32_e32 v81, 1.0, v81
	v_exp_f32_e32 v87, v87
	v_mul_f32_e32 v78, v80, v78
	v_mul_f32_e32 v79, v81, v79
	v_mul_f32_e32 v80, v68, v68
	v_mul_f32_e32 v81, v69, v69
	v_exp_f32_e32 v76, v76
	v_fma_f32 v80, -v80, s64, v150
	v_fma_f32 v81, -v81, s64, v150
	v_exp_f32_e32 v77, v77
	v_mul_f32_e32 v80, v68, v80
	v_mul_f32_e32 v81, v69, v81
	v_mul_f32_e32 v64, s60, v64
	v_mul_f32_e32 v65, s60, v65
	v_exp_f32_e32 v80, v80
	v_exp_f32_e32 v81, v81
	v_exp_f32_e32 v64, v64
	v_exp_f32_e32 v65, v65
	v_add_f32_e32 v82, 1.0, v86
	v_add_f32_e32 v83, 1.0, v87
	v_add_f32_e32 v76, 1.0, v76
	v_add_f32_e32 v77, 1.0, v77
	v_add_f32_e32 v80, 1.0, v80
	v_add_f32_e32 v81, 1.0, v81
	v_mul_f32_e32 v76, v82, v76
	v_mul_f32_e32 v77, v83, v77
	v_mul_f32_e32 v82, v70, v70
	v_mul_f32_e32 v83, v71, v71
	v_add_f32_e32 v64, 1.0, v64
	v_add_f32_e32 v65, 1.0, v65
	v_mul_f32_e32 v66, s60, v66
	v_mul_f32_e32 v67, s60, v67
	v_mul_f32_e32 v64, v80, v64
	v_mul_f32_e32 v65, v81, v65
	v_fma_f32 v80, -v82, s64, v150
	v_fma_f32 v81, -v83, s64, v150
	v_exp_f32_e32 v66, v66
	v_mul_f32_e32 v80, v70, v80
	v_mul_f32_e32 v81, v71, v81
	v_exp_f32_e32 v67, v67
	v_exp_f32_e32 v80, v80
	v_exp_f32_e32 v81, v81
	v_rcp_f32_e32 v64, v64
	v_add_f32_e32 v66, 1.0, v66
	v_add_f32_e32 v67, 1.0, v67
	v_rcp_f32_e32 v65, v65
	v_add_f32_e32 v80, 1.0, v80
	v_add_f32_e32 v81, 1.0, v81
	v_rcp_f32_e32 v76, v76
	v_mul_f32_e32 v66, v80, v66
	v_mul_f32_e32 v67, v81, v67
	v_rcp_f32_e32 v77, v77
	v_rcp_f32_e32 v78, v78
	v_rcp_f32_e32 v79, v79
	v_rcp_f32_e32 v66, v66
	v_rcp_f32_e32 v67, v67
	v_mul_f32_e32 v68, v68, v64
	v_mul_f32_e32 v69, v69, v65
; __device__ __forceinline__ u32x4 pack8(f32x4 v0, f32x4 v1) { u32x4 w; w.x = cvt_pk_bf16(v0[0], v0[1]); w.y = cvt_pk_bf16(v0[2], v0[3]); w.z = cvt_pk_bf16(v1[0], v1[1]); w.w = cvt_pk_bf16(v1[2], v1[3]); return w; }
; __device__ __forceinline__ f32x2 g1_2(f32x2 x, f32x2 g) { const f32x2 u = x * x, p = u * (0.044715f * -2.302208198f) + (-2.302208198f), t = x * p, tg = g * (-LOG2E);
;     f32x2 e1, e2; e1.x = __builtin_amdgcn_exp2f(t.x); e1.y = __builtin_amdgcn_exp2f(t.y); e2.x = __builtin_amdgcn_exp2f(tg.x); e2.y = __builtin_amdgcn_exp2f(tg.y);
;     const f32x2 d = (e1 + 1.0f) * (e2 + 1.0f); f32x2 r; r.x = __builtin_amdgcn_rcpf(d.x); r.y = __builtin_amdgcn_rcpf(d.y); return x * r; }
; __device__ __forceinline__ f32x4 g1_4(f32x4 v, f32x4 g) { const f32x2 a = g1_2((f32x2){v[0], v[1]}, (f32x2){g[0], g[1]}), b = g1_2((f32x2){v[2], v[3]}, (f32x2){g[2], g[3]}); return (f32x4){a.x, a.y, b.x, b.y}; }
; __device__ __forceinline__ f32x4 gelu4(f32x4 v) { const f32x2 a = gelu2((f32x2){v[0], v[1]}), b = gelu2((f32x2){v[2], v[3]}); return (f32x4){a.x, a.y, b.x, b.y}; }
; __device__ __forceinline__ f32x4 sigmoid4(f32x4 v) { const f32x2 a = sigmoid2((f32x2){v[0], v[1]}), b = sigmoid2((f32x2){v[2], v[3]}); return (f32x4){a.x, a.y, b.x, b.y}; }
;     __device__ __forceinline__ void operator()(const f32x4 (&acc)[2][2][4][2], const Unit& u, int ui, int wr, int wc, int fr, int fq) const {
;         const int pn = u.pn;
;         if (pn < 8) {
;             bf16_t* base = (bf16_t*)(ws + WS_U) + (size_t)(u.pm * 256 + wr * 64 + fr) * DM + pn * 128 + wc * 32 + 8 * fq;
; #pragma unroll
;             for (int ai = 0; ai < 2; ++ai)
; #pragma unroll
;                 for (int m = 0; m < 4; ++m) {
;                     const f32x4 g0 = g1_4(acc[ai][0][m][0], acc[ai][1][m][0]), g1 = g1_4(acc[ai][0][m][1], acc[ai][1][m][1]);
;                     *(u32x4*)(base + (size_t)(ai * 128 + m * 16) * DM) = pack8(g0, g1); }
	s_mov_b32 s6, 0x18000
	v_mul_f32_e32 v72, v72, v76
	v_mul_f32_e32 v73, v73, v77
	v_mul_f32_e32 v74, v74, v78
	v_mul_f32_e32 v75, v75, v79
	v_mul_f32_e32 v70, v70, v66
	v_mul_f32_e32 v71, v71, v67
	v_cvt_pk_bf16_f32 v64, v72, v73
	v_cvt_pk_bf16_f32 v65, v74, v75
	v_cvt_pk_bf16_f32 v66, v68, v69
	v_add_co_u32_e32 v68, vcc, s6, v124
	v_cvt_pk_bf16_f32 v67, v70, v71
	v_mul_f32_e32 v62, s60, v62
	v_mul_f32_e32 v63, s60, v63
	s_nop 0
	v_addc_co_u32_e32 v69, vcc, 0, v125, vcc
	global_store_dwordx4 v[68:69], v[64:67], off
	v_exp_f32_e32 v62, v62
	v_exp_f32_e32 v63, v63
	v_mul_f32_e32 v64, v58, v58
	v_mul_f32_e32 v65, v59, v59
	v_mul_f32_e32 v70, v56, v56
	v_mul_f32_e32 v71, v57, v57
	v_fma_f32 v64, -v64, s64, v150
	v_fma_f32 v65, -v65, s64, v150
	v_add_f32_e32 v62, 1.0, v62
	v_add_f32_e32 v63, 1.0, v63
	v_mul_f32_e32 v64, v58, v64
	v_mul_f32_e32 v65, v59, v65
	v_fma_f32 v70, -v70, s64, v150
	v_fma_f32 v71, -v71, s64, v150
	v_exp_f32_e32 v64, v64
	v_exp_f32_e32 v65, v65
	v_mul_f32_e32 v70, v56, v70
	v_mul_f32_e32 v71, v57, v71
	v_mul_f32_e32 v60, s60, v60
	v_mul_f32_e32 v61, s60, v61
	v_exp_f32_e32 v70, v70
	v_add_f32_e32 v64, 1.0, v64
	v_add_f32_e32 v65, 1.0, v65
	v_exp_f32_e32 v71, v71
	v_mul_f32_e32 v62, v64, v62
	v_mul_f32_e32 v63, v65, v63
	v_mul_f32_e32 v64, v52, v52
	v_mul_f32_e32 v65, v53, v53
	v_exp_f32_e32 v60, v60
	v_fma_f32 v64, -v64, s64, v150
	v_fma_f32 v65, -v65, s64, v150
	v_exp_f32_e32 v61, v61
	v_mul_f32_e32 v64, v52, v64
	v_mul_f32_e32 v65, v53, v65
	v_mul_f32_e32 v48, s60, v48
	v_mul_f32_e32 v49, s60, v49
	v_exp_f32_e32 v64, v64
	v_exp_f32_e32 v65, v65
	v_exp_f32_e32 v48, v48
	v_exp_f32_e32 v49, v49
	v_add_f32_e32 v66, 1.0, v70
	v_add_f32_e32 v67, 1.0, v71
	v_add_f32_e32 v60, 1.0, v60
	v_add_f32_e32 v61, 1.0, v61
	v_add_f32_e32 v64, 1.0, v64
	v_add_f32_e32 v65, 1.0, v65
	v_mul_f32_e32 v60, v66, v60
	v_mul_f32_e32 v61, v67, v61
	v_mul_f32_e32 v66, v54, v54
	v_mul_f32_e32 v67, v55, v55
	v_add_f32_e32 v48, 1.0, v48
	v_add_f32_e32 v49, 1.0, v49
	v_mul_f32_e32 v50, s60, v50
	v_mul_f32_e32 v51, s60, v51
	v_mul_f32_e32 v48, v64, v48
	v_mul_f32_e32 v49, v65, v49
	v_fma_f32 v64, -v66, s64, v150
	v_fma_f32 v65, -v67, s64, v150
	v_exp_f32_e32 v50, v50
	v_mul_f32_e32 v64, v54, v64
	v_mul_f32_e32 v65, v55, v65
	v_exp_f32_e32 v51, v51
	v_exp_f32_e32 v64, v64
	v_exp_f32_e32 v65, v65
	v_rcp_f32_e32 v48, v48
	v_add_f32_e32 v50, 1.0, v50
	v_add_f32_e32 v51, 1.0, v51
	v_rcp_f32_e32 v49, v49
	v_add_f32_e32 v64, 1.0, v64
	v_add_f32_e32 v65, 1.0, v65
	v_rcp_f32_e32 v60, v60
	v_mul_f32_e32 v50, v64, v50
	v_mul_f32_e32 v51, v65, v51
	v_rcp_f32_e32 v61, v61
	v_rcp_f32_e32 v62, v62
	v_rcp_f32_e32 v63, v63
	v_rcp_f32_e32 v50, v50
	v_rcp_f32_e32 v51, v51
	v_mul_f32_e32 v52, v52, v48
	v_mul_f32_e32 v53, v53, v49
	v_mul_f32_e32 v56, v56, v60
	v_mul_f32_e32 v57, v57, v61
	v_mul_f32_e32 v58, v58, v62
	v_mul_f32_e32 v59, v59, v63
	v_mul_f32_e32 v54, v54, v50
	v_mul_f32_e32 v55, v55, v51
	v_cvt_pk_bf16_f32 v48, v56, v57
	v_cvt_pk_bf16_f32 v49, v58, v59
	v_cvt_pk_bf16_f32 v50, v52, v53
	v_add_co_u32_e32 v52, vcc, s99, v124
	v_cvt_pk_bf16_f32 v51, v54, v55
	v_mul_f32_e32 v46, s60, v46
	v_mul_f32_e32 v47, s60, v47
	s_nop 0
	v_addc_co_u32_e32 v53, vcc, 0, v125, vcc
	global_store_dwordx4 v[52:53], v[48:51], off
	v_exp_f32_e32 v46, v46
	v_exp_f32_e32 v47, v47
	v_mul_f32_e32 v48, v42, v42
	v_mul_f32_e32 v49, v43, v43
	v_mul_f32_e32 v54, v40, v40
	v_mul_f32_e32 v55, v41, v41
	v_fma_f32 v48, -v48, s64, v150
	v_fma_f32 v49, -v49, s64, v150
	v_add_f32_e32 v46, 1.0, v46
	v_add_f32_e32 v47, 1.0, v47
	v_mul_f32_e32 v48, v42, v48
	v_mul_f32_e32 v49, v43, v49
	v_fma_f32 v54, -v54, s64, v150
	v_fma_f32 v55, -v55, s64, v150
	v_exp_f32_e32 v48, v48
	v_exp_f32_e32 v49, v49
	v_mul_f32_e32 v54, v40, v54
	v_mul_f32_e32 v55, v41, v55
	v_mul_f32_e32 v44, s60, v44
	v_mul_f32_e32 v45, s60, v45
	v_exp_f32_e32 v54, v54
	v_add_f32_e32 v48, 1.0, v48
	v_add_f32_e32 v49, 1.0, v49
	v_exp_f32_e32 v55, v55
	v_mul_f32_e32 v46, v48, v46
	v_mul_f32_e32 v47, v49, v47
	v_mul_f32_e32 v48, v36, v36
	v_mul_f32_e32 v49, v37, v37
	v_exp_f32_e32 v44, v44
	v_fma_f32 v48, -v48, s64, v150
	v_fma_f32 v49, -v49, s64, v150
	v_exp_f32_e32 v45, v45
	v_mul_f32_e32 v48, v36, v48
	v_mul_f32_e32 v49, v37, v49
	v_mul_f32_e32 v32, s60, v32
	v_mul_f32_e32 v33, s60, v33
	v_exp_f32_e32 v48, v48
	v_exp_f32_e32 v49, v49
	v_exp_f32_e32 v32, v32
	v_exp_f32_e32 v33, v33
	v_add_f32_e32 v50, 1.0, v54
	v_add_f32_e32 v51, 1.0, v55
	v_add_f32_e32 v44, 1.0, v44
	v_add_f32_e32 v45, 1.0, v45
	v_add_f32_e32 v48, 1.0, v48
	v_add_f32_e32 v49, 1.0, v49
	v_mul_f32_e32 v44, v50, v44
	v_mul_f32_e32 v45, v51, v45
	v_mul_f32_e32 v50, v38, v38
	v_mul_f32_e32 v51, v39, v39
	v_add_f32_e32 v32, 1.0, v32
	v_add_f32_e32 v33, 1.0, v33
	v_mul_f32_e32 v34, s60, v34
	v_mul_f32_e32 v35, s60, v35
	v_mul_f32_e32 v32, v48, v32
	v_mul_f32_e32 v33, v49, v33
	v_fma_f32 v48, -v50, s64, v150
	v_fma_f32 v49, -v51, s64, v150
	v_exp_f32_e32 v34, v34
	v_mul_f32_e32 v48, v38, v48
	v_mul_f32_e32 v49, v39, v49
	v_exp_f32_e32 v35, v35
	v_exp_f32_e32 v48, v48
	v_exp_f32_e32 v49, v49
	v_rcp_f32_e32 v32, v32
	v_add_f32_e32 v34, 1.0, v34
	v_add_f32_e32 v35, 1.0, v35
	v_rcp_f32_e32 v33, v33
	v_add_f32_e32 v48, 1.0, v48
	v_add_f32_e32 v49, 1.0, v49
	v_rcp_f32_e32 v44, v44
	v_mul_f32_e32 v34, v48, v34
	v_mul_f32_e32 v35, v49, v35
	v_rcp_f32_e32 v45, v45
	v_rcp_f32_e32 v46, v46
	v_rcp_f32_e32 v47, v47
	v_rcp_f32_e32 v34, v34
	v_rcp_f32_e32 v35, v35
	v_mul_f32_e32 v36, v36, v32
	v_mul_f32_e32 v37, v37, v33
	v_mul_f32_e32 v40, v40, v44
	v_mul_f32_e32 v41, v41, v45
	v_mul_f32_e32 v42, v42, v46
	v_mul_f32_e32 v43, v43, v47
	v_mul_f32_e32 v38, v38, v34
	v_mul_f32_e32 v39, v39, v35
; __device__ __forceinline__ u32x4 pack8(f32x4 v0, f32x4 v1) { u32x4 w; w.x = cvt_pk_bf16(v0[0], v0[1]); w.y = cvt_pk_bf16(v0[2], v0[3]); w.z = cvt_pk_bf16(v1[0], v1[1]); w.w = cvt_pk_bf16(v1[2], v1[3]); return w; }
; __device__ __forceinline__ f32x2 g1_2(f32x2 x, f32x2 g) { const f32x2 u = x * x, p = u * (0.044715f * -2.302208198f) + (-2.302208198f), t = x * p, tg = g * (-LOG2E);
;     f32x2 e1, e2; e1.x = __builtin_amdgcn_exp2f(t.x); e1.y = __builtin_amdgcn_exp2f(t.y); e2.x = __builtin_amdgcn_exp2f(tg.x); e2.y = __builtin_amdgcn_exp2f(tg.y);
;     const f32x2 d = (e1 + 1.0f) * (e2 + 1.0f); f32x2 r; r.x = __builtin_amdgcn_rcpf(d.x); r.y = __builtin_amdgcn_rcpf(d.y); return x * r; }
; __device__ __forceinline__ f32x4 g1_4(f32x4 v, f32x4 g) { const f32x2 a = g1_2((f32x2){v[0], v[1]}, (f32x2){g[0], g[1]}), b = g1_2((f32x2){v[2], v[3]}, (f32x2){g[2], g[3]}); return (f32x4){a.x, a.y, b.x, b.y}; }
; __device__ __forceinline__ f32x4 gelu4(f32x4 v) { const f32x2 a = gelu2((f32x2){v[0], v[1]}), b = gelu2((f32x2){v[2], v[3]}); return (f32x4){a.x, a.y, b.x, b.y}; }
; __device__ __forceinline__ f32x4 sigmoid4(f32x4 v) { const f32x2 a = sigmoid2((f32x2){v[0], v[1]}), b = sigmoid2((f32x2){v[2], v[3]}); return (f32x4){a.x, a.y, b.x, b.y}; }
;     __device__ __forceinline__ void operator()(const f32x4 (&acc)[2][2][4][2], const Unit& u, int ui, int wr, int wc, int fr, int fq) const {
;         const int pn = u.pn;
;         if (pn < 8) {
;             bf16_t* base = (bf16_t*)(ws + WS_U) + (size_t)(u.pm * 256 + wr * 64 + fr) * DM + pn * 128 + wc * 32 + 8 * fq;
; #pragma unroll
;             for (int ai = 0; ai < 2; ++ai)
; #pragma unroll
;                 for (int m = 0; m < 4; ++m) {
;                     const f32x4 g0 = g1_4(acc[ai][0][m][0], acc[ai][1][m][0]), g1 = g1_4(acc[ai][0][m][1], acc[ai][1][m][1]);
;                     *(u32x4*)(base + (size_t)(ai * 128 + m * 16) * DM) = pack8(g0, g1); }
	v_cvt_pk_bf16_f32 v32, v40, v41
	v_cvt_pk_bf16_f32 v33, v42, v43
	v_cvt_pk_bf16_f32 v34, v36, v37
	v_add_co_u32_e32 v36, vcc, s22, v124
	v_cvt_pk_bf16_f32 v35, v38, v39
	v_mul_f32_e32 v30, s60, v30
	v_mul_f32_e32 v31, s60, v31
	s_nop 0
	v_addc_co_u32_e32 v37, vcc, 0, v125, vcc
	global_store_dwordx4 v[36:37], v[32:35], off
	v_exp_f32_e32 v30, v30
	v_exp_f32_e32 v31, v31
	v_mul_f32_e32 v32, v26, v26
	v_mul_f32_e32 v33, v27, v27
	v_mul_f32_e32 v38, v24, v24
	v_mul_f32_e32 v39, v25, v25
	v_fma_f32 v32, -v32, s64, v150
	v_fma_f32 v33, -v33, s64, v150
	v_add_f32_e32 v30, 1.0, v30
	v_add_f32_e32 v31, 1.0, v31
	v_mul_f32_e32 v32, v26, v32
	v_mul_f32_e32 v33, v27, v33
	v_fma_f32 v38, -v38, s64, v150
	v_fma_f32 v39, -v39, s64, v150
	v_exp_f32_e32 v32, v32
	v_exp_f32_e32 v33, v33
	v_mul_f32_e32 v38, v24, v38
	v_mul_f32_e32 v39, v25, v39
	v_mul_f32_e32 v28, s60, v28
	v_mul_f32_e32 v29, s60, v29
	v_exp_f32_e32 v38, v38
	v_add_f32_e32 v32, 1.0, v32
	v_add_f32_e32 v33, 1.0, v33
	v_exp_f32_e32 v39, v39
	v_mul_f32_e32 v30, v32, v30
	v_mul_f32_e32 v31, v33, v31
	v_mul_f32_e32 v32, v20, v20
	v_mul_f32_e32 v33, v21, v21
	v_exp_f32_e32 v28, v28
	v_fma_f32 v32, -v32, s64, v150
	v_fma_f32 v33, -v33, s64, v150
	v_exp_f32_e32 v29, v29
	v_mul_f32_e32 v32, v20, v32
	v_mul_f32_e32 v33, v21, v33
	v_mul_f32_e32 v16, s60, v16
	v_mul_f32_e32 v17, s60, v17
	v_exp_f32_e32 v32, v32
	v_exp_f32_e32 v33, v33
	v_exp_f32_e32 v16, v16
	v_exp_f32_e32 v17, v17
	v_add_f32_e32 v34, 1.0, v38
	v_add_f32_e32 v35, 1.0, v39
	v_add_f32_e32 v28, 1.0, v28
	v_add_f32_e32 v29, 1.0, v29
	v_add_f32_e32 v32, 1.0, v32
	v_add_f32_e32 v33, 1.0, v33
	v_mul_f32_e32 v28, v34, v28
	v_mul_f32_e32 v29, v35, v29
	v_mul_f32_e32 v34, v22, v22
	v_mul_f32_e32 v35, v23, v23
	v_add_f32_e32 v16, 1.0, v16
	v_add_f32_e32 v17, 1.0, v17
	v_mul_f32_e32 v18, s60, v18
	v_mul_f32_e32 v19, s60, v19
	v_mul_f32_e32 v16, v32, v16
	v_mul_f32_e32 v17, v33, v17
	v_fma_f32 v32, -v34, s64, v150
	v_fma_f32 v33, -v35, s64, v150
	v_exp_f32_e32 v18, v18
	v_mul_f32_e32 v32, v22, v32
	v_mul_f32_e32 v33, v23, v33
	v_exp_f32_e32 v19, v19
	v_exp_f32_e32 v32, v32
	v_exp_f32_e32 v33, v33
	v_rcp_f32_e32 v16, v16
	v_add_f32_e32 v18, 1.0, v18
	v_add_f32_e32 v19, 1.0, v19
	v_rcp_f32_e32 v17, v17
	v_add_f32_e32 v32, 1.0, v32
	v_add_f32_e32 v33, 1.0, v33
	v_rcp_f32_e32 v28, v28
	v_mul_f32_e32 v18, v32, v18
	v_mul_f32_e32 v19, v33, v19
	v_rcp_f32_e32 v29, v29
	v_rcp_f32_e32 v30, v30
	v_rcp_f32_e32 v31, v31
	v_rcp_f32_e32 v18, v18
	v_rcp_f32_e32 v19, v19
	v_mul_f32_e32 v20, v20, v16
	v_mul_f32_e32 v21, v21, v17
	v_mul_f32_e32 v24, v24, v28
	v_mul_f32_e32 v25, v25, v29
	v_mul_f32_e32 v26, v26, v30
	v_mul_f32_e32 v27, v27, v31
	v_mul_f32_e32 v22, v22, v18
	v_mul_f32_e32 v23, v23, v19
	v_cvt_pk_bf16_f32 v16, v24, v25
	v_cvt_pk_bf16_f32 v17, v26, v27
	v_cvt_pk_bf16_f32 v18, v20, v21
	v_add_co_u32_e32 v20, vcc, s23, v124
	v_cvt_pk_bf16_f32 v19, v22, v23
	v_mul_f32_e32 v14, s60, v14
	v_mul_f32_e32 v15, s60, v15
	s_nop 0
	v_addc_co_u32_e32 v21, vcc, 0, v125, vcc
	global_store_dwordx4 v[20:21], v[16:19], off
	v_exp_f32_e32 v14, v14
	v_exp_f32_e32 v15, v15
	v_mul_f32_e32 v16, v10, v10
	v_mul_f32_e32 v17, v11, v11
	v_mul_f32_e32 v22, v8, v8
	v_mul_f32_e32 v23, v9, v9
	v_fma_f32 v16, -v16, s64, v150
	v_fma_f32 v17, -v17, s64, v150
	v_add_f32_e32 v14, 1.0, v14
	v_add_f32_e32 v15, 1.0, v15
	v_mul_f32_e32 v16, v10, v16
	v_mul_f32_e32 v17, v11, v17
	v_fma_f32 v22, -v22, s64, v150
	v_fma_f32 v23, -v23, s64, v150
	v_exp_f32_e32 v16, v16
	v_exp_f32_e32 v17, v17
	v_mul_f32_e32 v22, v8, v22
	v_mul_f32_e32 v23, v9, v23
	v_mul_f32_e32 v12, s60, v12
	v_mul_f32_e32 v13, s60, v13
	v_exp_f32_e32 v22, v22
	v_add_f32_e32 v16, 1.0, v16
	v_add_f32_e32 v17, 1.0, v17
	v_exp_f32_e32 v23, v23
	v_mul_f32_e32 v14, v16, v14
	v_mul_f32_e32 v15, v17, v15
	v_mul_f32_e32 v16, v4, v4
	v_mul_f32_e32 v17, v5, v5
	v_exp_f32_e32 v12, v12
	v_fma_f32 v16, -v16, s64, v150
	v_fma_f32 v17, -v17, s64, v150
	v_exp_f32_e32 v13, v13
	v_mul_f32_e32 v16, v4, v16
	v_mul_f32_e32 v17, v5, v17
	v_mul_f32_e32 v0, s60, v0
	v_mul_f32_e32 v1, s60, v1
	v_exp_f32_e32 v16, v16
	v_exp_f32_e32 v17, v17
	v_exp_f32_e32 v0, v0
	v_exp_f32_e32 v1, v1
	v_add_f32_e32 v18, 1.0, v22
	v_add_f32_e32 v19, 1.0, v23
	v_add_f32_e32 v12, 1.0, v12
	v_add_f32_e32 v13, 1.0, v13
	v_add_f32_e32 v16, 1.0, v16
	v_add_f32_e32 v17, 1.0, v17
	v_mul_f32_e32 v12, v18, v12
	v_mul_f32_e32 v13, v19, v13
	v_mul_f32_e32 v18, v6, v6
	v_mul_f32_e32 v19, v7, v7
	v_add_f32_e32 v0, 1.0, v0
	v_add_f32_e32 v1, 1.0, v1
	v_mul_f32_e32 v2, s60, v2
	v_mul_f32_e32 v3, s60, v3
	v_mul_f32_e32 v0, v16, v0
	v_mul_f32_e32 v1, v17, v1
	v_fma_f32 v16, -v18, s64, v150
	v_fma_f32 v17, -v19, s64, v150
	v_exp_f32_e32 v2, v2
	v_mul_f32_e32 v16, v6, v16
	v_mul_f32_e32 v17, v7, v17
	v_exp_f32_e32 v3, v3
	v_exp_f32_e32 v16, v16
	v_exp_f32_e32 v17, v17
	v_rcp_f32_e32 v0, v0
	v_add_f32_e32 v2, 1.0, v2
	v_add_f32_e32 v3, 1.0, v3
	v_rcp_f32_e32 v1, v1
	v_add_f32_e32 v16, 1.0, v16
	v_add_f32_e32 v17, 1.0, v17
	v_rcp_f32_e32 v12, v12
	v_mul_f32_e32 v2, v16, v2
	v_mul_f32_e32 v3, v17, v3
	v_rcp_f32_e32 v13, v13
	v_rcp_f32_e32 v14, v14
	v_rcp_f32_e32 v15, v15
	v_rcp_f32_e32 v2, v2
	v_rcp_f32_e32 v3, v3
	v_mul_f32_e32 v4, v4, v0
	v_mul_f32_e32 v5, v5, v1
	v_mul_f32_e32 v8, v8, v12
	v_mul_f32_e32 v9, v9, v13
	v_mul_f32_e32 v10, v10, v14
	v_mul_f32_e32 v11, v11, v15
	v_mul_f32_e32 v6, v6, v2
	v_mul_f32_e32 v7, v7, v3
	v_cvt_pk_bf16_f32 v0, v8, v9
	v_cvt_pk_bf16_f32 v1, v10, v11
	v_cvt_pk_bf16_f32 v2, v4, v5
	v_add_co_u32_e32 v4, vcc, 0x58000, v124
	v_cvt_pk_bf16_f32 v3, v6, v7
	s_nop 1
	v_addc_co_u32_e32 v5, vcc, 0, v125, vcc
	global_store_dwordx4 v[4:5], v[0:3], off
	s_branch .LBB0_121

; __device__ __forceinline__ unsigned xb_ld(unsigned* p)              { return __hip_atomic_load(p, __ATOMIC_RELAXED, __HIP_MEMORY_SCOPE_AGENT); }
; __device__ __forceinline__ void xcd_barrier_complete(unsigned* bar, unsigned x, unsigned& nloc, unsigned& nx) {
;     const unsigned G = gridDim.x * gridDim.y * gridDim.z;
;     unsigned sum, cnt, mine, sp = 0u;
;     for (;;) {
;         sum = 0u; cnt = 0u; mine = 0u;
; #pragma unroll
;         for (unsigned j = 0; j < 16; ++j) { const unsigned c = xb_ld(&bar[XB_XCNT(j)]); sum += c; cnt += (c > 0u) ? 1u : 0u; mine = (j == x) ? c : mine; }
; __device__ __forceinline__ void xcd_barrier(const XcdBarrier& b) {
;     asm volatile("s_waitcnt vmcnt(0)" ::: "memory");
;     __syncthreads();
;     if (threadIdx.x == 0) {
;         unsigned* bar = b.bar;
;         __builtin_amdgcn_s_waitcnt(0);
;         unsigned nloc = b.st[0], nx = b.st[1];
;         if (nloc == 0u) { xcd_barrier_complete(bar, b.x, nloc, nx); b.st[0] = nloc; b.st[1] = nx; }
.LBB0_195:
	s_nop 0
	s_cmp_gt_i32 s31, 2
	s_cselect_b64 s[0:1], -1, 0
	s_and_b64 s[4:5], s[18:19], s[0:1]
	s_andn2_b64 vcc, exec, s[4:5]
	s_cbranch_vccnz .LBB0_245
	s_waitcnt vmcnt(0)
	s_waitcnt vmcnt(0) lgkmcnt(0)
	s_barrier
	s_and_saveexec_b64 s[4:5], s[8:9]
	s_cbranch_execz .LBB0_244
	s_add_i32 s6, 0, 0x25ff0
	v_mov_b32_e32 v0, s6
	s_waitcnt vmcnt(0) expcnt(0) lgkmcnt(0)
	ds_read_b32 v2, v0
	s_add_i32 s6, 0, 0x25ff4
	v_mov_b32_e32 v0, s6
	ds_read_b32 v0, v0
	s_waitcnt lgkmcnt(1)
	v_cmp_ne_u32_e32 vcc, 0, v2
	s_cbranch_vccnz .LBB0_212
	s_load_dwordx2 s[18:19], s[52:53], 0x4
	s_add_u32 s6, s28, 0x3e800200
	s_addc_u32 s7, s29, 0
	s_add_u32 s10, s28, 0x3e800400
	s_addc_u32 s11, s29, 0
	s_waitcnt lgkmcnt(0)
	s_mul_i32 s76, s18, s3
	s_add_u32 s18, s28, 0x3e800500
	s_mul_i32 s76, s76, s19
	s_addc_u32 s19, s29, 0
	s_add_u32 s20, s28, 0x3e800600
	s_addc_u32 s21, s29, 0
	s_add_u32 s22, s28, 0x3e800700
	s_addc_u32 s23, s29, 0
	s_add_u32 s24, s28, 0x3e800800
	s_addc_u32 s25, s29, 0
	s_add_u32 s42, s28, 0x3e800900
	s_addc_u32 s43, s29, 0
	s_add_u32 s44, s28, 0x3e800a00
	s_addc_u32 s45, s29, 0
	s_add_u32 s48, s28, 0x3e800b00
	s_addc_u32 s49, s29, 0
	s_add_u32 s54, s28, 0x3e800c00
	s_addc_u32 s55, s29, 0
	s_add_u32 s56, s28, 0x3e800d00
	s_addc_u32 s57, s29, 0
	s_add_u32 s58, s28, 0x3e800e00
	s_addc_u32 s59, s29, 0
	s_add_u32 s60, s28, 0x3e800f00
	s_addc_u32 s61, s29, 0
	s_add_u32 s62, s28, 0x3e801000
	s_addc_u32 s63, s29, 0
	s_add_u32 s64, s28, 0x3e801100
	s_addc_u32 s65, s29, 0
	s_add_u32 s66, s28, 0x3e801200
	s_addc_u32 s67, s29, 0
	s_add_u32 s68, s28, 0x3e801300
	s_addc_u32 s69, s29, 0
	s_mov_b32 s77, 1
	v_mov_b32_e32 v16, 0
	s_branch .LBB0_200
